# attention: last two PV MFMAs of each tile moved behind the barrier and the next tile's K reads (fills K-read latency), on top of v25
# baseline (speedup 1.0000x reference)
; #define SBAR() __builtin_amdgcn_sched_barrier(0)
; __device__ __forceinline__ void finishSM(f32x16& p0, f32x16& p1, float alpha, float& l_reg, bf16x8& pa0, bf16x8& pa1, bf16x8& pa2, bf16x8& pa3) {
;   for (int r = 0; r < 16; ++r) p1[r] = __builtin_amdgcn_exp2f(p1[r]);
;   float ps = 0; for (int r = 0; r < 16; ++r) ps += p0[r]; for (int r = 0; r < 16; ++r) ps += p1[r];
;   { auto rr = __builtin_amdgcn_permlane32_swap(__float_as_uint(ps), __float_as_uint(ps), false, false);
;     ps = __uint_as_float(rr[0]) + __uint_as_float(rr[1]); }
;   l_reg = l_reg * alpha + ps;
;     ...
;   PK4(p0, 0, pa0); PK4(p0, 8, pa1); PK4(p1, 0, pa2); PK4(p1, 8, pa3);
;     ...
; }
; template <int BOFF> __device__ __forceinline__ void qkt_i(f32x16& p0, f32x16& p1, const int (&kb)[4], const bf16x8* qr) {
;   p0 = f32x16{}; p1 = f32x16{};
; #pragma unroll
;   for (int d0 = 0; d0 < 8; ++d0) { const int off = BOFF + (d0 >> 2) * 128;
;     const bf16x8 b0 = LDSV(kb[d0 & 3] + off), b1 = LDSV(kb[d0 & 3] + off + 8192);
;     p0 = __builtin_amdgcn_mfma_f32_32x32x16_bf16(b0, qr[d0], p0, 0, 0, 0);
;     p1 = __builtin_amdgcn_mfma_f32_32x32x16_bf16(b1, qr[d0], p1, 0, 0, 0); }
; }
; template <int D0, int BOFF> __device__ __forceinline__ void pv_one_i(f32x16& od, int vb, bf16x8 pa0, bf16x8 pa1, bf16x8 pa2, bf16x8 pa3) {
;   const s16x4 l0 = tr_read<BOFF + v_rd_off(D0, 0, 0)>(vb), h0 = tr_read<BOFF + v_rd_off(D0, 0, 1)>(vb), l1 = tr_read<BOFF + v_rd_off(D0, 1, 0)>(vb), h1 = tr_read<BOFF + v_rd_off(D0, 1, 1)>(vb);
;   const s16x4 l2 = tr_read<BOFF + v_rd_off(D0, 2, 0)>(vb), h2 = tr_read<BOFF + v_rd_off(D0, 2, 1)>(vb), l3 = tr_read<BOFF + v_rd_off(D0, 3, 0)>(vb), h3 = tr_read<BOFF + v_rd_off(D0, 3, 1)>(vb);
;   asm volatile("s_waitcnt lgkmcnt(0)" ::: "memory"); SBAR();
;     ...
;   od = __builtin_amdgcn_mfma_f32_32x32x16_bf16(pa0, PK(l0, h0), od, 0, 0, 0);
;   od = __builtin_amdgcn_mfma_f32_32x32x16_bf16(pa1, PK(l1, h1), od, 0, 0, 0);
;   od = __builtin_amdgcn_mfma_f32_32x32x16_bf16(pa2, PK(l2, h2), od, 0, 0, 0);
;   od = __builtin_amdgcn_mfma_f32_32x32x16_bf16(pa3, PK(l3, h3), od, 0, 0, 0);
;     ...
; }
; template <int BOFF> __device__ __forceinline__ void pv_i(f32x16* o, int vb, bf16x8 pa0, bf16x8 pa1, bf16x8 pa2, bf16x8 pa3) {
;   pv_one_i<0, BOFF>(o[0], vb, pa0, pa1, pa2, pa3); pv_one_i<1, BOFF>(o[1], vb, pa0, pa1, pa2, pa3); pv_one_i<2, BOFF>(o[2], vb, pa0, pa1, pa2, pa3); pv_one_i<3, BOFF>(o[3], vb, pa0, pa1, pa2, pa3);
; }
.LBB0_352:
	s_waitcnt lgkmcnt(0)
	s_barrier
	ds_read_b128 v[80:83], v207 offset:16384
	ds_read_b128 v[84:87], v207 offset:24576
	ds_read_b128 v[162:165], v208 offset:16384
	ds_read_b128 v[166:169], v208 offset:24576
	v_exp_f32_e32 v170, v72
	v_exp_f32_e32 v171, v73
	v_exp_f32_e32 v172, v74
	v_exp_f32_e32 v173, v75
	v_exp_f32_e32 v174, v76
	v_exp_f32_e32 v175, v77
	v_exp_f32_e32 v176, v78
	v_exp_f32_e32 v79, v79
	s_waitcnt lgkmcnt(3)
	v_mfma_f32_32x32x16_bf16 v[96:111], v[80:83], v[142:145], 0
	v_exp_f32_e32 v236, v64
	v_add_f32_e32 v64, 0, v229
	v_add_f32_e32 v64, v243, v64
	v_add_f32_e32 v64, v244, v64
	s_waitcnt lgkmcnt(2)
	v_mfma_f32_32x32x16_bf16 v[80:95], v[84:87], v[142:145], 0
	v_add_f32_e32 v64, v246, v64
	v_add_f32_e32 v64, v242, v64
	v_add_f32_e32 v64, v245, v64
	s_waitcnt lgkmcnt(1)
	v_mfma_f32_32x32x16_bf16 v[96:111], v[162:165], v[138:141], v[96:111]
	v_add_f32_e32 v64, v227, v64
	v_add_f32_e32 v64, v228, v64
	v_add_f32_e32 v64, v223, v64
	s_waitcnt lgkmcnt(0)
	v_mfma_f32_32x32x16_bf16 v[80:95], v[166:169], v[138:141], v[80:95]
	ds_read_b128 v[162:165], v209 offset:16384
	ds_read_b128 v[166:169], v209 offset:24576
	v_add_f32_e32 v64, v226, v64
	v_add_f32_e32 v64, v224, v64
	v_add_f32_e32 v64, v225, v64
	v_add_f32_e32 v64, v220, v64
	v_exp_f32_e32 v237, v65
	s_waitcnt lgkmcnt(1)
	v_mfma_f32_32x32x16_bf16 v[96:111], v[162:165], v[112:115], v[96:111]
	v_add_f32_e32 v64, v222, v64
	v_exp_f32_e32 v238, v66
	v_add_f32_e32 v64, v219, v64
	v_exp_f32_e32 v239, v67
	s_waitcnt lgkmcnt(0)
	v_mfma_f32_32x32x16_bf16 v[80:95], v[166:169], v[112:115], v[80:95]
	ds_read_b128 v[162:165], v210 offset:16384
	ds_read_b128 v[166:169], v210 offset:24576
	v_add_f32_e32 v64, v221, v64
	v_exp_f32_e32 v247, v68
	v_add_f32_e32 v64, v236, v64
	v_exp_f32_e32 v248, v69
	s_waitcnt lgkmcnt(1)
	v_mfma_f32_32x32x16_bf16 v[96:111], v[162:165], v[116:119], v[96:111]
	v_add_f32_e32 v64, v237, v64
	v_exp_f32_e32 v249, v70
	v_add_f32_e32 v64, v238, v64
	v_exp_f32_e32 v252, v71
	s_waitcnt lgkmcnt(0)
	v_mfma_f32_32x32x16_bf16 v[80:95], v[166:169], v[116:119], v[80:95]
	ds_read_b128 v[162:165], v190 offset:16384
	ds_read_b128 v[166:169], v190 offset:24576
	v_add_f32_e32 v64, v239, v64
	v_add_f32_e32 v64, v247, v64
	v_add_f32_e32 v64, v248, v64
	v_add_f32_e32 v64, v249, v64
	v_add_f32_e32 v64, v252, v64
	v_add_f32_e32 v64, v170, v64
	s_waitcnt lgkmcnt(1)
	v_mfma_f32_32x32x16_bf16 v[96:111], v[162:165], v[120:123], v[96:111]
	v_add_f32_e32 v64, v171, v64
	v_add_f32_e32 v64, v172, v64
	v_add_f32_e32 v64, v173, v64
	v_add_f32_e32 v64, v174, v64
	v_add_f32_e32 v64, v175, v64
	s_waitcnt lgkmcnt(0)
	v_mfma_f32_32x32x16_bf16 v[80:95], v[166:169], v[120:123], v[80:95]
	ds_read_b128 v[162:165], v191 offset:16384
	ds_read_b128 v[166:169], v191 offset:24576
	v_add_f32_e32 v64, v176, v64
	v_add_f32_e32 v64, v79, v64
	v_mov_b32_e32 v65, v64
	s_nop 1
	v_permlane32_swap_b32_e32 v64, v65
	v_add_f32_e32 v64, v64, v65
	s_waitcnt lgkmcnt(1)
	v_mfma_f32_32x32x16_bf16 v[96:111], v[162:165], v[124:127], v[96:111]
	v_add_f32_e32 v128, v215, v64
	v_cvt_pk_bf16_f32 v64, v229, v243
	v_cvt_pk_bf16_f32 v65, v244, v246
	v_cvt_pk_bf16_f32 v66, v242, v245
	v_cvt_pk_bf16_f32 v67, v227, v228
	s_waitcnt lgkmcnt(0)
	v_mfma_f32_32x32x16_bf16 v[80:95], v[166:169], v[124:127], v[80:95]
	ds_read_b128 v[162:165], v192 offset:16384
	ds_read_b128 v[166:169], v192 offset:24576
	v_cvt_pk_bf16_f32 v68, v223, v226
	v_cvt_pk_bf16_f32 v69, v224, v225
	v_cvt_pk_bf16_f32 v70, v220, v222
	v_cvt_pk_bf16_f32 v71, v219, v221
	v_cvt_pk_bf16_f32 v72, v236, v237
	v_cvt_pk_bf16_f32 v73, v238, v239
	s_waitcnt lgkmcnt(1)
	v_mfma_f32_32x32x16_bf16 v[96:111], v[162:165], v[130:133], v[96:111]
	v_cvt_pk_bf16_f32 v74, v247, v248
	v_cvt_pk_bf16_f32 v75, v249, v252
	v_cvt_pk_bf16_f32 v76, v170, v171
	v_cvt_pk_bf16_f32 v77, v172, v173
	v_cvt_pk_bf16_f32 v78, v174, v175
	s_waitcnt lgkmcnt(0)
	v_mfma_f32_32x32x16_bf16 v[80:95], v[166:169], v[130:133], v[80:95]
	ds_read_b128 v[162:165], v193 offset:16384
	ds_read_b128 v[166:169], v193 offset:24576
	ds_read_b64_tr_b16 v[180:181], v206 offset:0
	ds_read_b64_tr_b16 v[182:183], v206 offset:0x800
	ds_read_b64_tr_b16 v[184:185], v206 offset:0x1000
	ds_read_b64_tr_b16 v[186:187], v206 offset:0x1800
	ds_read_b64_tr_b16 v[216:217], v206 offset:0x2000
	ds_read_b64_tr_b16 v[218:219], v206 offset:0x2800
	ds_read_b64_tr_b16 v[220:221], v206 offset:0x3000
	ds_read_b64_tr_b16 v[222:223], v206 offset:0x3800
	v_cvt_pk_bf16_f32 v79, v176, v79
	s_nop 0
	v_permlane32_swap_b32_e32 v64, v66
	v_permlane32_swap_b32_e32 v65, v67
	v_permlane32_swap_b32_e32 v68, v70
	v_permlane32_swap_b32_e32 v69, v71
	s_waitcnt lgkmcnt(9)
	v_mfma_f32_32x32x16_bf16 v[96:111], v[162:165], v[134:137], v[96:111]
	v_permlane32_swap_b32_e32 v72, v74
	v_permlane32_swap_b32_e32 v73, v75
	v_permlane32_swap_b32_e32 v76, v78
	v_permlane32_swap_b32_e32 v77, v79
	s_waitcnt lgkmcnt(8)
	v_mfma_f32_32x32x16_bf16 v[80:95], v[166:169], v[134:137], v[80:95]
	v_add_co_u32_e32 v166, vcc, s19, v178
	s_nop 1
	v_addc_co_u32_e32 v167, vcc, -1, v179, vcc
	v_add_co_u32_e32 v170, vcc, s20, v178
	s_nop 1
	v_addc_co_u32_e32 v171, vcc, -1, v179, vcc
	global_load_dwordx4 v[162:165], v[166:167], off
	s_nop 0
	global_load_dwordx4 v[166:169], v[166:167], off offset:-512
	s_nop 0
	global_load_dwordx4 v[174:177], v[170:171], off
	s_nop 0
	global_load_dwordx4 v[170:173], v[170:171], off offset:-512
	s_waitcnt vmcnt(4)
	ds_write_b128 v211, v[146:149] offset:32768
	s_nop 0
	s_waitcnt lgkmcnt(7)
	v_mfma_f32_32x32x16_bf16 v[0:15], v[64:67], v[180:183], v[0:15]
	ds_read_b64_tr_b16 v[180:181], v206 offset:0x200
	ds_read_b64_tr_b16 v[182:183], v206 offset:0xa00
	s_waitcnt lgkmcnt(7)
; #define SBAR() __builtin_amdgcn_sched_barrier(0)
; template <int D0, int BOFF> __device__ __forceinline__ void pv_one_i(f32x16& od, int vb, bf16x8 pa0, bf16x8 pa1, bf16x8 pa2, bf16x8 pa3) {
;   const s16x4 l0 = tr_read<BOFF + v_rd_off(D0, 0, 0)>(vb), h0 = tr_read<BOFF + v_rd_off(D0, 0, 1)>(vb), l1 = tr_read<BOFF + v_rd_off(D0, 1, 0)>(vb), h1 = tr_read<BOFF + v_rd_off(D0, 1, 1)>(vb);
;   const s16x4 l2 = tr_read<BOFF + v_rd_off(D0, 2, 0)>(vb), h2 = tr_read<BOFF + v_rd_off(D0, 2, 1)>(vb), l3 = tr_read<BOFF + v_rd_off(D0, 3, 0)>(vb), h3 = tr_read<BOFF + v_rd_off(D0, 3, 1)>(vb);
;   asm volatile("s_waitcnt lgkmcnt(0)" ::: "memory"); SBAR();
;     ...
;   od = __builtin_amdgcn_mfma_f32_32x32x16_bf16(pa0, PK(l0, h0), od, 0, 0, 0);
;   od = __builtin_amdgcn_mfma_f32_32x32x16_bf16(pa1, PK(l1, h1), od, 0, 0, 0);
;   od = __builtin_amdgcn_mfma_f32_32x32x16_bf16(pa2, PK(l2, h2), od, 0, 0, 0);
;   od = __builtin_amdgcn_mfma_f32_32x32x16_bf16(pa3, PK(l3, h3), od, 0, 0, 0);
;     ...
; }
; template <int BOFF> __device__ __forceinline__ void pv_i(f32x16* o, int vb, bf16x8 pa0, bf16x8 pa1, bf16x8 pa2, bf16x8 pa3) {
;   pv_one_i<0, BOFF>(o[0], vb, pa0, pa1, pa2, pa3); pv_one_i<1, BOFF>(o[1], vb, pa0, pa1, pa2, pa3); pv_one_i<2, BOFF>(o[2], vb, pa0, pa1, pa2, pa3); pv_one_i<3, BOFF>(o[3], vb, pa0, pa1, pa2, pa3);
; }
	v_mfma_f32_32x32x16_bf16 v[0:15], v[68:71], v[184:187], v[0:15]
	ds_read_b64_tr_b16 v[184:185], v206 offset:0x1200
	ds_read_b64_tr_b16 v[186:187], v206 offset:0x1a00
	s_waitcnt lgkmcnt(7)
	v_mfma_f32_32x32x16_bf16 v[0:15], v[72:75], v[216:219], v[0:15]
	ds_read_b64_tr_b16 v[216:217], v206 offset:0x2200
	ds_read_b64_tr_b16 v[218:219], v206 offset:0x2a00
	s_waitcnt lgkmcnt(7)
	v_mfma_f32_32x32x16_bf16 v[0:15], v[76:79], v[220:223], v[0:15]
	ds_read_b64_tr_b16 v[220:221], v206 offset:0x3200
	ds_read_b64_tr_b16 v[222:223], v206 offset:0x3a00
	ds_write_b128 v212, v[150:153] offset:32768
	s_waitcnt lgkmcnt(7)
	v_mfma_f32_32x32x16_bf16 v[16:31], v[64:67], v[180:183], v[16:31]
	ds_read_b64_tr_b16 v[180:181], v206 offset:0x400
	ds_read_b64_tr_b16 v[182:183], v206 offset:0xc00
	s_waitcnt lgkmcnt(7)
	v_mfma_f32_32x32x16_bf16 v[16:31], v[68:71], v[184:187], v[16:31]
	ds_read_b64_tr_b16 v[184:185], v206 offset:0x1400
	ds_read_b64_tr_b16 v[186:187], v206 offset:0x1c00
	s_waitcnt lgkmcnt(7)
	v_mfma_f32_32x32x16_bf16 v[16:31], v[72:75], v[216:219], v[16:31]
	ds_read_b64_tr_b16 v[216:217], v206 offset:0x2400
	ds_read_b64_tr_b16 v[218:219], v206 offset:0x2c00
	s_waitcnt lgkmcnt(7)
	v_mfma_f32_32x32x16_bf16 v[16:31], v[76:79], v[220:223], v[16:31]
	ds_read_b64_tr_b16 v[220:221], v206 offset:0x3400
	ds_read_b64_tr_b16 v[222:223], v206 offset:0x3c00
	ds_write_b128 v213, v[154:157] offset:32768
	s_waitcnt lgkmcnt(7)
	v_mfma_f32_32x32x16_bf16 v[32:47], v[64:67], v[180:183], v[32:47]
	ds_read_b64_tr_b16 v[180:181], v206 offset:0x600
	ds_read_b64_tr_b16 v[182:183], v206 offset:0xe00
	s_waitcnt lgkmcnt(7)
	v_mfma_f32_32x32x16_bf16 v[32:47], v[68:71], v[184:187], v[32:47]
	ds_read_b64_tr_b16 v[184:185], v206 offset:0x1600
	ds_read_b64_tr_b16 v[186:187], v206 offset:0x1e00
	s_waitcnt lgkmcnt(7)
	v_mfma_f32_32x32x16_bf16 v[32:47], v[72:75], v[216:219], v[32:47]
	ds_read_b64_tr_b16 v[216:217], v206 offset:0x2600
	ds_read_b64_tr_b16 v[218:219], v206 offset:0x2e00
	s_waitcnt lgkmcnt(7)
	v_mfma_f32_32x32x16_bf16 v[32:47], v[76:79], v[220:223], v[32:47]
	ds_read_b64_tr_b16 v[220:221], v206 offset:0x3600
	ds_read_b64_tr_b16 v[222:223], v206 offset:0x3e00
	ds_write_b128 v214, v[158:161] offset:32768
	s_waitcnt lgkmcnt(7)
	v_mfma_f32_32x32x16_bf16 v[48:63], v[64:67], v[180:183], v[48:63]
	v_exp_f32_e32 v215, v108
	s_waitcnt vmcnt(4)
	v_exp_f32_e32 v181, v96
	v_exp_f32_e32 v183, v97
	v_exp_f32_e32 v188, v102
	v_exp_f32_e32 v189, v103
	v_exp_f32_e32 v196, v104
	s_waitcnt lgkmcnt(5)
	v_mfma_f32_32x32x16_bf16 v[48:63], v[68:71], v[184:187], v[48:63]
	v_exp_f32_e32 v184, v98
	v_exp_f32_e32 v185, v99
	v_exp_f32_e32 v186, v100
	v_exp_f32_e32 v187, v101
	v_exp_f32_e32 v197, v105
	v_exp_f32_e32 v198, v106
	v_exp_f32_e32 v199, v107
	s_waitcnt lgkmcnt(0)
	s_barrier
	ds_read_b128 v[64:67], v207 offset:32768
	ds_read_b128 v[96:99], v207 offset:40960
	ds_read_b128 v[146:149], v208 offset:32768
	ds_read_b128 v[150:153], v208 offset:40960
	v_mfma_f32_32x32x16_bf16 v[48:63], v[72:75], v[216:219], v[48:63]
	v_mfma_f32_32x32x16_bf16 v[48:63], v[76:79], v[220:223], v[48:63]
	v_exp_f32_e32 v216, v109
	v_exp_f32_e32 v217, v110
	v_exp_f32_e32 v218, v111
	v_exp_f32_e32 v154, v88
	v_exp_f32_e32 v155, v89
	v_exp_f32_e32 v156, v90
	v_exp_f32_e32 v157, v91
	v_exp_f32_e32 v158, v92
	v_exp_f32_e32 v159, v93
	v_exp_f32_e32 v160, v94
	v_exp_f32_e32 v95, v95
	s_waitcnt lgkmcnt(3)
	v_mfma_f32_32x32x16_bf16 v[64:79], v[64:67], v[142:145], 0
	v_exp_f32_e32 v236, v80
	v_add_f32_e32 v80, 0, v181
	v_add_f32_e32 v80, v183, v80
	v_add_f32_e32 v80, v184, v80
	s_waitcnt lgkmcnt(2)
	v_mfma_f32_32x32x16_bf16 v[96:111], v[96:99], v[142:145], 0
	v_add_f32_e32 v80, v185, v80
	v_add_f32_e32 v80, v186, v80
	v_add_f32_e32 v80, v187, v80
	s_waitcnt lgkmcnt(1)
	v_mfma_f32_32x32x16_bf16 v[64:79], v[146:149], v[138:141], v[64:79]
	v_add_f32_e32 v80, v188, v80
	v_add_f32_e32 v80, v189, v80
	v_add_f32_e32 v80, v196, v80
	s_waitcnt lgkmcnt(0)
	v_mfma_f32_32x32x16_bf16 v[96:111], v[150:153], v[138:141], v[96:111]
	ds_read_b128 v[146:149], v209 offset:32768
	ds_read_b128 v[150:153], v209 offset:40960
	v_add_f32_e32 v80, v197, v80
	v_add_f32_e32 v80, v198, v80
	v_add_f32_e32 v80, v199, v80
	v_add_f32_e32 v80, v215, v80
	v_exp_f32_e32 v237, v81
	s_waitcnt lgkmcnt(1)
	v_mfma_f32_32x32x16_bf16 v[64:79], v[146:149], v[112:115], v[64:79]
	v_add_f32_e32 v80, v216, v80
	v_exp_f32_e32 v238, v82
	v_add_f32_e32 v80, v217, v80
	v_exp_f32_e32 v239, v83
	s_waitcnt lgkmcnt(0)
	v_mfma_f32_32x32x16_bf16 v[96:111], v[150:153], v[112:115], v[96:111]
	ds_read_b128 v[146:149], v210 offset:32768
	ds_read_b128 v[150:153], v210 offset:40960
	v_add_f32_e32 v80, v218, v80
	v_exp_f32_e32 v247, v84
	v_add_f32_e32 v80, v236, v80
	v_exp_f32_e32 v248, v85
	s_waitcnt lgkmcnt(1)
	v_mfma_f32_32x32x16_bf16 v[64:79], v[146:149], v[116:119], v[64:79]
	v_add_f32_e32 v80, v237, v80
	v_exp_f32_e32 v249, v86
	v_add_f32_e32 v80, v238, v80
	v_exp_f32_e32 v252, v87
	s_waitcnt lgkmcnt(0)
	v_mfma_f32_32x32x16_bf16 v[96:111], v[150:153], v[116:119], v[96:111]
	ds_read_b128 v[146:149], v190 offset:32768
	ds_read_b128 v[150:153], v190 offset:40960
	v_add_f32_e32 v80, v239, v80
	v_add_f32_e32 v80, v247, v80
	v_add_f32_e32 v80, v248, v80
	v_add_f32_e32 v80, v249, v80
	v_add_f32_e32 v80, v252, v80
	v_add_f32_e32 v80, v154, v80
	s_waitcnt lgkmcnt(1)
	v_mfma_f32_32x32x16_bf16 v[64:79], v[146:149], v[120:123], v[64:79]
	v_add_f32_e32 v80, v155, v80
	v_add_f32_e32 v80, v156, v80
	v_add_f32_e32 v80, v157, v80
	v_add_f32_e32 v80, v158, v80
	v_add_f32_e32 v80, v159, v80
	s_waitcnt lgkmcnt(0)
; #define SBAR() __builtin_amdgcn_sched_barrier(0)
; template <int D0, int BOFF> __device__ __forceinline__ void pv_one_i(f32x16& od, int vb, bf16x8 pa0, bf16x8 pa1, bf16x8 pa2, bf16x8 pa3) {
;   const s16x4 l0 = tr_read<BOFF + v_rd_off(D0, 0, 0)>(vb), h0 = tr_read<BOFF + v_rd_off(D0, 0, 1)>(vb), l1 = tr_read<BOFF + v_rd_off(D0, 1, 0)>(vb), h1 = tr_read<BOFF + v_rd_off(D0, 1, 1)>(vb);
;   const s16x4 l2 = tr_read<BOFF + v_rd_off(D0, 2, 0)>(vb), h2 = tr_read<BOFF + v_rd_off(D0, 2, 1)>(vb), l3 = tr_read<BOFF + v_rd_off(D0, 3, 0)>(vb), h3 = tr_read<BOFF + v_rd_off(D0, 3, 1)>(vb);
;   asm volatile("s_waitcnt lgkmcnt(0)" ::: "memory"); SBAR();
;     ...
;   od = __builtin_amdgcn_mfma_f32_32x32x16_bf16(pa0, PK(l0, h0), od, 0, 0, 0);
;   od = __builtin_amdgcn_mfma_f32_32x32x16_bf16(pa1, PK(l1, h1), od, 0, 0, 0);
;   od = __builtin_amdgcn_mfma_f32_32x32x16_bf16(pa2, PK(l2, h2), od, 0, 0, 0);
;   od = __builtin_amdgcn_mfma_f32_32x32x16_bf16(pa3, PK(l3, h3), od, 0, 0, 0);
;     ...
; }
; template <int BOFF> __device__ __forceinline__ void pv_i(f32x16* o, int vb, bf16x8 pa0, bf16x8 pa1, bf16x8 pa2, bf16x8 pa3) {
;   pv_one_i<0, BOFF>(o[0], vb, pa0, pa1, pa2, pa3); pv_one_i<1, BOFF>(o[1], vb, pa0, pa1, pa2, pa3); pv_one_i<2, BOFF>(o[2], vb, pa0, pa1, pa2, pa3); pv_one_i<3, BOFF>(o[3], vb, pa0, pa1, pa2, pa3);
; }
	v_mfma_f32_32x32x16_bf16 v[96:111], v[150:153], v[120:123], v[96:111]
	ds_read_b128 v[146:149], v191 offset:32768
	ds_read_b128 v[150:153], v191 offset:40960
	v_add_f32_e32 v80, v160, v80
	v_add_f32_e32 v180, v95, v80
	v_mov_b32_e32 v182, v180
	v_cvt_pk_bf16_f32 v80, v181, v183
	v_cvt_pk_bf16_f32 v81, v184, v185
	v_cvt_pk_bf16_f32 v82, v186, v187
	s_waitcnt lgkmcnt(1)
	v_mfma_f32_32x32x16_bf16 v[64:79], v[146:149], v[124:127], v[64:79]
	v_cvt_pk_bf16_f32 v83, v188, v189
	v_cvt_pk_bf16_f32 v84, v196, v197
	v_cvt_pk_bf16_f32 v85, v198, v199
	v_cvt_pk_bf16_f32 v86, v215, v216
	v_cvt_pk_bf16_f32 v87, v217, v218
	s_waitcnt lgkmcnt(0)
	v_mfma_f32_32x32x16_bf16 v[96:111], v[150:153], v[124:127], v[96:111]
	ds_read_b128 v[146:149], v192 offset:32768
	ds_read_b128 v[150:153], v192 offset:40960
	v_cvt_pk_bf16_f32 v88, v236, v237
	v_cvt_pk_bf16_f32 v89, v238, v239
	v_cvt_pk_bf16_f32 v90, v247, v248
	v_cvt_pk_bf16_f32 v91, v249, v252
	v_cvt_pk_bf16_f32 v92, v154, v155
	v_cvt_pk_bf16_f32 v93, v156, v157
	s_waitcnt lgkmcnt(1)
	v_mfma_f32_32x32x16_bf16 v[64:79], v[146:149], v[130:133], v[64:79]
	v_cvt_pk_bf16_f32 v94, v158, v159
	v_cvt_pk_bf16_f32 v95, v160, v95
	s_nop 1
	v_permlane32_swap_b32_e32 v180, v182
	v_permlane32_swap_b32_e32 v80, v82
	s_waitcnt lgkmcnt(0)
	v_mfma_f32_32x32x16_bf16 v[96:111], v[150:153], v[130:133], v[96:111]
	ds_read_b128 v[146:149], v193 offset:32768
	ds_read_b128 v[150:153], v193 offset:40960
	ds_read_b64_tr_b16 v[184:185], v206 offset:0x4000
	ds_read_b64_tr_b16 v[186:187], v206 offset:0x4800
	ds_read_b64_tr_b16 v[216:217], v206 offset:0x5000
	ds_read_b64_tr_b16 v[218:219], v206 offset:0x5800
	ds_read_b64_tr_b16 v[220:221], v206 offset:0x6000
	ds_read_b64_tr_b16 v[222:223], v206 offset:0x6800
	ds_read_b64_tr_b16 v[224:225], v206 offset:0x7000
	ds_read_b64_tr_b16 v[226:227], v206 offset:0x7800
	v_permlane32_swap_b32_e32 v81, v83
	v_permlane32_swap_b32_e32 v84, v86
	v_permlane32_swap_b32_e32 v85, v87
	v_permlane32_swap_b32_e32 v88, v90
	v_permlane32_swap_b32_e32 v89, v91
	v_permlane32_swap_b32_e32 v92, v94
	s_waitcnt lgkmcnt(9)
	v_mfma_f32_32x32x16_bf16 v[64:79], v[146:149], v[134:137], v[64:79]
	v_permlane32_swap_b32_e32 v93, v95
	s_waitcnt lgkmcnt(8)
	v_mfma_f32_32x32x16_bf16 v[96:111], v[150:153], v[134:137], v[96:111]
	v_add_co_u32_e32 v150, vcc, s21, v178
	s_nop 1
	v_addc_co_u32_e32 v151, vcc, -1, v179, vcc
	v_add_co_u32_e32 v154, vcc, s22, v178
	s_nop 1
	v_addc_co_u32_e32 v155, vcc, -1, v179, vcc
	global_load_dwordx4 v[146:149], v[150:151], off
	s_nop 0
	global_load_dwordx4 v[150:153], v[150:151], off offset:-512
	s_nop 0
	global_load_dwordx4 v[158:161], v[154:155], off
	s_nop 0
	global_load_dwordx4 v[154:157], v[154:155], off offset:-512
	s_waitcnt vmcnt(4)
	ds_write_b128 v211, v[162:165]
	s_nop 0
	s_waitcnt lgkmcnt(7)
	v_mfma_f32_32x32x16_bf16 v[0:15], v[80:83], v[184:187], v[0:15]
	ds_read_b64_tr_b16 v[184:185], v206 offset:0x4200
	ds_read_b64_tr_b16 v[186:187], v206 offset:0x4a00
	s_waitcnt lgkmcnt(7)
	v_mfma_f32_32x32x16_bf16 v[0:15], v[84:87], v[216:219], v[0:15]
	ds_read_b64_tr_b16 v[216:217], v206 offset:0x5200
	ds_read_b64_tr_b16 v[218:219], v206 offset:0x5a00
	s_waitcnt lgkmcnt(7)
	v_mfma_f32_32x32x16_bf16 v[0:15], v[88:91], v[220:223], v[0:15]
	ds_read_b64_tr_b16 v[220:221], v206 offset:0x6200
	ds_read_b64_tr_b16 v[222:223], v206 offset:0x6a00
	s_waitcnt lgkmcnt(7)
	v_mfma_f32_32x32x16_bf16 v[0:15], v[92:95], v[224:227], v[0:15]
	ds_read_b64_tr_b16 v[224:225], v206 offset:0x7200
	ds_read_b64_tr_b16 v[226:227], v206 offset:0x7a00
	ds_write_b128 v212, v[174:177]
	s_waitcnt lgkmcnt(7)
	v_mfma_f32_32x32x16_bf16 v[16:31], v[80:83], v[184:187], v[16:31]
	ds_read_b64_tr_b16 v[184:185], v206 offset:0x4400
	ds_read_b64_tr_b16 v[186:187], v206 offset:0x4c00
	s_waitcnt lgkmcnt(7)
	v_mfma_f32_32x32x16_bf16 v[16:31], v[84:87], v[216:219], v[16:31]
	ds_read_b64_tr_b16 v[216:217], v206 offset:0x5400
	ds_read_b64_tr_b16 v[218:219], v206 offset:0x5c00
	s_waitcnt lgkmcnt(7)
	v_mfma_f32_32x32x16_bf16 v[16:31], v[88:91], v[220:223], v[16:31]
	ds_read_b64_tr_b16 v[220:221], v206 offset:0x6400
	ds_read_b64_tr_b16 v[222:223], v206 offset:0x6c00
	s_waitcnt lgkmcnt(7)
	v_mfma_f32_32x32x16_bf16 v[16:31], v[92:95], v[224:227], v[16:31]
	ds_read_b64_tr_b16 v[224:225], v206 offset:0x7400
	ds_read_b64_tr_b16 v[226:227], v206 offset:0x7c00
	ds_write_b128 v213, v[166:169]
	s_waitcnt lgkmcnt(7)
	v_mfma_f32_32x32x16_bf16 v[32:47], v[80:83], v[184:187], v[32:47]
	ds_read_b64_tr_b16 v[184:185], v206 offset:0x4600
	ds_read_b64_tr_b16 v[186:187], v206 offset:0x4e00
	s_waitcnt lgkmcnt(7)
	v_mfma_f32_32x32x16_bf16 v[32:47], v[84:87], v[216:219], v[32:47]
	ds_read_b64_tr_b16 v[216:217], v206 offset:0x5600
	ds_read_b64_tr_b16 v[218:219], v206 offset:0x5e00
	s_waitcnt lgkmcnt(7)
	v_mfma_f32_32x32x16_bf16 v[32:47], v[88:91], v[220:223], v[32:47]
	ds_read_b64_tr_b16 v[220:221], v206 offset:0x6600
	ds_read_b64_tr_b16 v[222:223], v206 offset:0x6e00
	s_waitcnt lgkmcnt(7)
	v_mfma_f32_32x32x16_bf16 v[32:47], v[92:95], v[224:227], v[32:47]
	ds_read_b64_tr_b16 v[224:225], v206 offset:0x7600
	ds_read_b64_tr_b16 v[226:227], v206 offset:0x7e00
	ds_write_b128 v214, v[170:173]
	s_waitcnt lgkmcnt(7)
	v_mfma_f32_32x32x16_bf16 v[48:63], v[80:83], v[184:187], v[48:63]
	v_exp_f32_e32 v215, v74
	s_waitcnt vmcnt(4)
	v_exp_f32_e32 v184, v64
	v_exp_f32_e32 v185, v65
	v_exp_f32_e32 v186, v66
	v_exp_f32_e32 v187, v67
	v_exp_f32_e32 v188, v68
	s_waitcnt lgkmcnt(5)
	v_mfma_f32_32x32x16_bf16 v[48:63], v[84:87], v[216:219], v[48:63]
	v_exp_f32_e32 v219, v78
	v_exp_f32_e32 v189, v69
	v_exp_f32_e32 v196, v70
	v_exp_f32_e32 v197, v71
	v_exp_f32_e32 v198, v72
	v_exp_f32_e32 v199, v73
	v_exp_f32_e32 v216, v75
	s_waitcnt lgkmcnt(0)
	s_barrier
; template <int BOFF> __device__ __forceinline__ void qkt_i(f32x16& p0, f32x16& p1, const int (&kb)[4], const bf16x8* qr) {
;   p0 = f32x16{}; p1 = f32x16{};
; #pragma unroll
;   for (int d0 = 0; d0 < 8; ++d0) { const int off = BOFF + (d0 >> 2) * 128;
;     const bf16x8 b0 = LDSV(kb[d0 & 3] + off), b1 = LDSV(kb[d0 & 3] + off + 8192);
;     p0 = __builtin_amdgcn_mfma_f32_32x32x16_bf16(b0, qr[d0], p0, 0, 0, 0);
;     p1 = __builtin_amdgcn_mfma_f32_32x32x16_bf16(b1, qr[d0], p1, 0, 0, 0); }
; }
	ds_read_b128 v[64:67], v207
	ds_read_b128 v[68:71], v207 offset:8192
	ds_read_b128 v[162:165], v208
	ds_read_b128 v[166:169], v208 offset:8192
	v_mfma_f32_32x32x16_bf16 v[48:63], v[88:91], v[220:223], v[48:63]
	v_mfma_f32_32x32x16_bf16 v[48:63], v[92:95], v[224:227], v[48:63]
	v_exp_f32_e32 v220, v79
	v_exp_f32_e32 v217, v76
	v_exp_f32_e32 v218, v77
	v_exp_f32_e32 v170, v104
	v_exp_f32_e32 v171, v105
	v_exp_f32_e32 v172, v106
	v_exp_f32_e32 v173, v107
	v_exp_f32_e32 v174, v108
	v_exp_f32_e32 v175, v109
	v_exp_f32_e32 v176, v110
	v_exp_f32_e32 v111, v111
	s_waitcnt lgkmcnt(3)
	v_mfma_f32_32x32x16_bf16 v[80:95], v[64:67], v[142:145], 0
	v_exp_f32_e32 v236, v96
	v_add_f32_e32 v96, 0, v184
	v_add_f32_e32 v96, v185, v96
	v_add_f32_e32 v96, v186, v96
	s_waitcnt lgkmcnt(2)
	v_mfma_f32_32x32x16_bf16 v[64:79], v[68:71], v[142:145], 0
	v_add_f32_e32 v96, v187, v96
	v_add_f32_e32 v96, v188, v96
	v_add_f32_e32 v96, v189, v96
	s_waitcnt lgkmcnt(1)
	v_mfma_f32_32x32x16_bf16 v[80:95], v[162:165], v[138:141], v[80:95]
	v_add_f32_e32 v96, v196, v96
	v_add_f32_e32 v96, v197, v96
	v_add_f32_e32 v96, v198, v96
	s_waitcnt lgkmcnt(0)
	v_mfma_f32_32x32x16_bf16 v[64:79], v[166:169], v[138:141], v[64:79]
	ds_read_b128 v[162:165], v209
	ds_read_b128 v[166:169], v209 offset:8192
	v_add_f32_e32 v96, v199, v96
	v_add_f32_e32 v96, v215, v96
	v_add_f32_e32 v96, v216, v96
	v_add_f32_e32 v96, v217, v96
	v_exp_f32_e32 v237, v97
	s_waitcnt lgkmcnt(1)
	v_mfma_f32_32x32x16_bf16 v[80:95], v[162:165], v[112:115], v[80:95]
	v_add_f32_e32 v96, v218, v96
	v_exp_f32_e32 v238, v98
	v_add_f32_e32 v96, v219, v96
	v_exp_f32_e32 v239, v99
	s_waitcnt lgkmcnt(0)
	v_mfma_f32_32x32x16_bf16 v[64:79], v[166:169], v[112:115], v[64:79]
	ds_read_b128 v[162:165], v210
	ds_read_b128 v[166:169], v210 offset:8192
	v_add_f32_e32 v96, v220, v96
	v_exp_f32_e32 v247, v100
	v_add_f32_e32 v96, v236, v96
	v_exp_f32_e32 v248, v101
	s_waitcnt lgkmcnt(1)
	v_mfma_f32_32x32x16_bf16 v[80:95], v[162:165], v[116:119], v[80:95]
	v_add_f32_e32 v96, v237, v96
	v_exp_f32_e32 v249, v102
	v_add_f32_e32 v96, v238, v96
	v_exp_f32_e32 v252, v103
	s_waitcnt lgkmcnt(0)
	v_mfma_f32_32x32x16_bf16 v[64:79], v[166:169], v[116:119], v[64:79]
	ds_read_b128 v[162:165], v190 offset:0
	ds_read_b128 v[166:169], v190 offset:8192
	v_add_f32_e32 v96, v239, v96
	v_add_f32_e32 v96, v247, v96
	v_add_f32_e32 v96, v248, v96
	v_add_f32_e32 v96, v249, v96
	v_add_f32_e32 v96, v252, v96
	v_add_f32_e32 v96, v170, v96
	s_waitcnt lgkmcnt(1)
	v_mfma_f32_32x32x16_bf16 v[80:95], v[162:165], v[120:123], v[80:95]
	v_add_f32_e32 v96, v171, v96
	v_add_f32_e32 v96, v172, v96
	v_add_f32_e32 v96, v173, v96
	v_add_f32_e32 v96, v174, v96
	v_add_f32_e32 v96, v175, v96
	s_waitcnt lgkmcnt(0)
	v_mfma_f32_32x32x16_bf16 v[64:79], v[166:169], v[120:123], v[64:79]
	ds_read_b128 v[162:165], v191 offset:0
	ds_read_b128 v[166:169], v191 offset:8192
	v_add_f32_e32 v96, v176, v96
	v_add_f32_e32 v181, v111, v96
	v_mov_b32_e32 v183, v181
	s_nop 1
	v_permlane32_swap_b32_e32 v181, v183
	v_pk_add_f32 v[96:97], v[180:181], v[182:183]
	s_waitcnt lgkmcnt(1)
	v_mfma_f32_32x32x16_bf16 v[80:95], v[162:165], v[124:127], v[80:95]
	s_nop 0
	v_add_f32_e32 v96, v128, v96
	v_add_f32_e32 v128, v96, v97
	v_cvt_pk_bf16_f32 v96, v184, v185
	v_cvt_pk_bf16_f32 v97, v186, v187
	s_waitcnt lgkmcnt(0)
	v_mfma_f32_32x32x16_bf16 v[64:79], v[166:169], v[124:127], v[64:79]
	ds_read_b128 v[162:165], v192 offset:0
	ds_read_b128 v[166:169], v192 offset:8192
	v_cvt_pk_bf16_f32 v98, v188, v189
	v_cvt_pk_bf16_f32 v99, v196, v197
	v_cvt_pk_bf16_f32 v100, v198, v199
	v_cvt_pk_bf16_f32 v101, v215, v216
	v_cvt_pk_bf16_f32 v102, v217, v218
	v_cvt_pk_bf16_f32 v103, v219, v220
	s_waitcnt lgkmcnt(1)
	v_mfma_f32_32x32x16_bf16 v[80:95], v[162:165], v[130:133], v[80:95]
	v_cvt_pk_bf16_f32 v104, v236, v237
	v_cvt_pk_bf16_f32 v105, v238, v239
	v_cvt_pk_bf16_f32 v106, v247, v248
	v_cvt_pk_bf16_f32 v107, v249, v252
	v_cvt_pk_bf16_f32 v108, v170, v171
	s_waitcnt lgkmcnt(0)
	v_mfma_f32_32x32x16_bf16 v[64:79], v[166:169], v[130:133], v[64:79]
	ds_read_b128 v[162:165], v193 offset:0
	ds_read_b128 v[166:169], v193 offset:8192
	ds_read_b64_tr_b16 v[180:181], v206 offset:0x8000
	ds_read_b64_tr_b16 v[182:183], v206 offset:0x8800
	ds_read_b64_tr_b16 v[184:185], v206 offset:0x9000
	ds_read_b64_tr_b16 v[186:187], v206 offset:0x9800
	ds_read_b64_tr_b16 v[216:217], v206 offset:0xa000
	ds_read_b64_tr_b16 v[218:219], v206 offset:0xa800
	ds_read_b64_tr_b16 v[220:221], v206 offset:0xb000
	ds_read_b64_tr_b16 v[222:223], v206 offset:0xb800
	v_cvt_pk_bf16_f32 v109, v172, v173
	v_cvt_pk_bf16_f32 v110, v174, v175
	v_cvt_pk_bf16_f32 v111, v176, v111
	s_nop 0
	v_permlane32_swap_b32_e32 v96, v98
	v_permlane32_swap_b32_e32 v97, v99
	s_waitcnt lgkmcnt(9)
	v_mfma_f32_32x32x16_bf16 v[80:95], v[162:165], v[134:137], v[80:95]
	v_permlane32_swap_b32_e32 v100, v102
	v_permlane32_swap_b32_e32 v101, v103
	v_permlane32_swap_b32_e32 v104, v106
	v_permlane32_swap_b32_e32 v105, v107
	v_permlane32_swap_b32_e32 v108, v110
	s_waitcnt lgkmcnt(8)
	v_mfma_f32_32x32x16_bf16 v[64:79], v[166:169], v[134:137], v[64:79]
	v_permlane32_swap_b32_e32 v109, v111
	v_add_co_u32_e32 v166, vcc, s23, v178
	s_nop 1
	v_addc_co_u32_e32 v167, vcc, -1, v179, vcc
	v_add_co_u32_e32 v170, vcc, s24, v178
	s_nop 1
	v_addc_co_u32_e32 v171, vcc, -1, v179, vcc
	global_load_dwordx4 v[162:165], v[166:167], off
	s_nop 0
	global_load_dwordx4 v[166:169], v[166:167], off offset:-512
	s_nop 0
	global_load_dwordx4 v[174:177], v[170:171], off
	s_nop 0
	global_load_dwordx4 v[170:173], v[170:171], off offset:-512
	s_waitcnt vmcnt(4)
	ds_write_b128 v211, v[146:149] offset:16384
	s_nop 0
	s_waitcnt lgkmcnt(7)
; #define SBAR() __builtin_amdgcn_sched_barrier(0)
; template <int D0, int BOFF> __device__ __forceinline__ void pv_one_i(f32x16& od, int vb, bf16x8 pa0, bf16x8 pa1, bf16x8 pa2, bf16x8 pa3) {
;   const s16x4 l0 = tr_read<BOFF + v_rd_off(D0, 0, 0)>(vb), h0 = tr_read<BOFF + v_rd_off(D0, 0, 1)>(vb), l1 = tr_read<BOFF + v_rd_off(D0, 1, 0)>(vb), h1 = tr_read<BOFF + v_rd_off(D0, 1, 1)>(vb);
;   const s16x4 l2 = tr_read<BOFF + v_rd_off(D0, 2, 0)>(vb), h2 = tr_read<BOFF + v_rd_off(D0, 2, 1)>(vb), l3 = tr_read<BOFF + v_rd_off(D0, 3, 0)>(vb), h3 = tr_read<BOFF + v_rd_off(D0, 3, 1)>(vb);
;   asm volatile("s_waitcnt lgkmcnt(0)" ::: "memory"); SBAR();
;     ...
;   od = __builtin_amdgcn_mfma_f32_32x32x16_bf16(pa0, PK(l0, h0), od, 0, 0, 0);
;   od = __builtin_amdgcn_mfma_f32_32x32x16_bf16(pa1, PK(l1, h1), od, 0, 0, 0);
;   od = __builtin_amdgcn_mfma_f32_32x32x16_bf16(pa2, PK(l2, h2), od, 0, 0, 0);
;   od = __builtin_amdgcn_mfma_f32_32x32x16_bf16(pa3, PK(l3, h3), od, 0, 0, 0);
;     ...
; }
; template <int BOFF> __device__ __forceinline__ void pv_i(f32x16* o, int vb, bf16x8 pa0, bf16x8 pa1, bf16x8 pa2, bf16x8 pa3) {
;   pv_one_i<0, BOFF>(o[0], vb, pa0, pa1, pa2, pa3); pv_one_i<1, BOFF>(o[1], vb, pa0, pa1, pa2, pa3); pv_one_i<2, BOFF>(o[2], vb, pa0, pa1, pa2, pa3); pv_one_i<3, BOFF>(o[3], vb, pa0, pa1, pa2, pa3);
; }
	v_mfma_f32_32x32x16_bf16 v[0:15], v[96:99], v[180:183], v[0:15]
	ds_read_b64_tr_b16 v[180:181], v206 offset:0x8200
	ds_read_b64_tr_b16 v[182:183], v206 offset:0x8a00
	s_waitcnt lgkmcnt(7)
	v_mfma_f32_32x32x16_bf16 v[0:15], v[100:103], v[184:187], v[0:15]
	ds_read_b64_tr_b16 v[184:185], v206 offset:0x9200
	ds_read_b64_tr_b16 v[186:187], v206 offset:0x9a00
	s_waitcnt lgkmcnt(7)
	v_mfma_f32_32x32x16_bf16 v[0:15], v[104:107], v[216:219], v[0:15]
	ds_read_b64_tr_b16 v[216:217], v206 offset:0xa200
	ds_read_b64_tr_b16 v[218:219], v206 offset:0xaa00
	s_waitcnt lgkmcnt(7)
	v_mfma_f32_32x32x16_bf16 v[0:15], v[108:111], v[220:223], v[0:15]
	ds_read_b64_tr_b16 v[220:221], v206 offset:0xb200
	ds_read_b64_tr_b16 v[222:223], v206 offset:0xba00
	ds_write_b128 v212, v[158:161] offset:16384
	s_waitcnt lgkmcnt(7)
	v_mfma_f32_32x32x16_bf16 v[16:31], v[96:99], v[180:183], v[16:31]
	ds_read_b64_tr_b16 v[180:181], v206 offset:0x8400
	ds_read_b64_tr_b16 v[182:183], v206 offset:0x8c00
	s_waitcnt lgkmcnt(7)
	v_mfma_f32_32x32x16_bf16 v[16:31], v[100:103], v[184:187], v[16:31]
	ds_read_b64_tr_b16 v[184:185], v206 offset:0x9400
	ds_read_b64_tr_b16 v[186:187], v206 offset:0x9c00
	s_waitcnt lgkmcnt(7)
	v_mfma_f32_32x32x16_bf16 v[16:31], v[104:107], v[216:219], v[16:31]
	ds_read_b64_tr_b16 v[216:217], v206 offset:0xa400
	ds_read_b64_tr_b16 v[218:219], v206 offset:0xac00
	s_waitcnt lgkmcnt(7)
	v_mfma_f32_32x32x16_bf16 v[16:31], v[108:111], v[220:223], v[16:31]
	ds_read_b64_tr_b16 v[220:221], v206 offset:0xb400
	ds_read_b64_tr_b16 v[222:223], v206 offset:0xbc00
	ds_write_b128 v213, v[150:153] offset:16384
	s_waitcnt lgkmcnt(7)
	v_mfma_f32_32x32x16_bf16 v[32:47], v[96:99], v[180:183], v[32:47]
	ds_read_b64_tr_b16 v[180:181], v206 offset:0x8600
	ds_read_b64_tr_b16 v[182:183], v206 offset:0x8e00
	s_waitcnt lgkmcnt(7)
	v_mfma_f32_32x32x16_bf16 v[32:47], v[100:103], v[184:187], v[32:47]
	ds_read_b64_tr_b16 v[184:185], v206 offset:0x9600
	ds_read_b64_tr_b16 v[186:187], v206 offset:0x9e00
	s_waitcnt lgkmcnt(7)
	v_mfma_f32_32x32x16_bf16 v[32:47], v[104:107], v[216:219], v[32:47]
	ds_read_b64_tr_b16 v[216:217], v206 offset:0xa600
	ds_read_b64_tr_b16 v[218:219], v206 offset:0xae00
	s_waitcnt lgkmcnt(7)
	v_mfma_f32_32x32x16_bf16 v[32:47], v[108:111], v[220:223], v[32:47]
	ds_read_b64_tr_b16 v[220:221], v206 offset:0xb600
	ds_read_b64_tr_b16 v[222:223], v206 offset:0xbe00
	ds_write_b128 v214, v[154:157] offset:16384
	s_waitcnt lgkmcnt(7)
	v_mfma_f32_32x32x16_bf16 v[48:63], v[96:99], v[180:183], v[48:63]
	v_exp_f32_e32 v215, v92
	s_waitcnt vmcnt(4)
	v_exp_f32_e32 v181, v80
	v_exp_f32_e32 v183, v81
	v_exp_f32_e32 v188, v86
	v_exp_f32_e32 v189, v87
	v_exp_f32_e32 v196, v88
	s_waitcnt lgkmcnt(5)
	v_mfma_f32_32x32x16_bf16 v[48:63], v[100:103], v[184:187], v[48:63]
	v_exp_f32_e32 v184, v82
	v_exp_f32_e32 v185, v83
	v_exp_f32_e32 v186, v84
	v_exp_f32_e32 v187, v85
	v_exp_f32_e32 v197, v89
	v_exp_f32_e32 v198, v90
	v_exp_f32_e32 v199, v91
	s_waitcnt lgkmcnt(0)
	s_barrier
	ds_read_b128 v[80:83], v207 offset:16384
	ds_read_b128 v[96:99], v207 offset:24576
	ds_read_b128 v[146:149], v208 offset:16384
	ds_read_b128 v[150:153], v208 offset:24576
	v_mfma_f32_32x32x16_bf16 v[48:63], v[104:107], v[216:219], v[48:63]
	v_mfma_f32_32x32x16_bf16 v[48:63], v[108:111], v[220:223], v[48:63]
	v_exp_f32_e32 v216, v93
	v_exp_f32_e32 v217, v94
	v_exp_f32_e32 v218, v95
	v_exp_f32_e32 v154, v72
	v_exp_f32_e32 v155, v73
	v_exp_f32_e32 v156, v74
	v_exp_f32_e32 v157, v75
	v_exp_f32_e32 v158, v76
	v_exp_f32_e32 v159, v77
	v_exp_f32_e32 v160, v78
	v_exp_f32_e32 v79, v79
	s_waitcnt lgkmcnt(3)
	v_mfma_f32_32x32x16_bf16 v[80:95], v[80:83], v[142:145], 0
	v_exp_f32_e32 v236, v64
	v_add_f32_e32 v64, 0, v181
	v_add_f32_e32 v64, v183, v64
	v_add_f32_e32 v64, v184, v64
	s_waitcnt lgkmcnt(2)
	v_mfma_f32_32x32x16_bf16 v[96:111], v[96:99], v[142:145], 0
	v_add_f32_e32 v64, v185, v64
	v_add_f32_e32 v64, v186, v64
	v_add_f32_e32 v64, v187, v64
	s_waitcnt lgkmcnt(1)
	v_mfma_f32_32x32x16_bf16 v[80:95], v[146:149], v[138:141], v[80:95]
	v_add_f32_e32 v64, v188, v64
	v_add_f32_e32 v64, v189, v64
	v_add_f32_e32 v64, v196, v64
	s_waitcnt lgkmcnt(0)
	v_mfma_f32_32x32x16_bf16 v[96:111], v[150:153], v[138:141], v[96:111]
	ds_read_b128 v[146:149], v209 offset:16384
	ds_read_b128 v[150:153], v209 offset:24576
	v_add_f32_e32 v64, v197, v64
	v_add_f32_e32 v64, v198, v64
	v_add_f32_e32 v64, v199, v64
	v_add_f32_e32 v64, v215, v64
	v_exp_f32_e32 v237, v65
	s_waitcnt lgkmcnt(1)
	v_mfma_f32_32x32x16_bf16 v[80:95], v[146:149], v[112:115], v[80:95]
	v_add_f32_e32 v64, v216, v64
	v_exp_f32_e32 v238, v66
	v_add_f32_e32 v64, v217, v64
	v_exp_f32_e32 v239, v67
	s_waitcnt lgkmcnt(0)
	v_mfma_f32_32x32x16_bf16 v[96:111], v[150:153], v[112:115], v[96:111]
	ds_read_b128 v[146:149], v210 offset:16384
	ds_read_b128 v[150:153], v210 offset:24576
	v_add_f32_e32 v64, v218, v64
	v_exp_f32_e32 v247, v68
	v_add_f32_e32 v64, v236, v64
	v_exp_f32_e32 v248, v69
	s_waitcnt lgkmcnt(1)
	v_mfma_f32_32x32x16_bf16 v[80:95], v[146:149], v[116:119], v[80:95]
	v_add_f32_e32 v64, v237, v64
	v_exp_f32_e32 v249, v70
	v_add_f32_e32 v64, v238, v64
	v_exp_f32_e32 v252, v71
	s_waitcnt lgkmcnt(0)
	v_mfma_f32_32x32x16_bf16 v[96:111], v[150:153], v[116:119], v[96:111]
	ds_read_b128 v[146:149], v190 offset:16384
	ds_read_b128 v[150:153], v190 offset:24576
	v_add_f32_e32 v64, v239, v64
	v_add_f32_e32 v64, v247, v64
	v_add_f32_e32 v64, v248, v64
	v_add_f32_e32 v64, v249, v64
	v_add_f32_e32 v64, v252, v64
	v_add_f32_e32 v64, v154, v64
	s_waitcnt lgkmcnt(1)
	v_mfma_f32_32x32x16_bf16 v[80:95], v[146:149], v[120:123], v[80:95]
	v_add_f32_e32 v64, v155, v64
	v_add_f32_e32 v64, v156, v64
	v_add_f32_e32 v64, v157, v64
	v_add_f32_e32 v64, v158, v64
	v_add_f32_e32 v64, v159, v64
	s_waitcnt lgkmcnt(0)
; #define SBAR() __builtin_amdgcn_sched_barrier(0)
; template <int D0, int BOFF> __device__ __forceinline__ void pv_one_i(f32x16& od, int vb, bf16x8 pa0, bf16x8 pa1, bf16x8 pa2, bf16x8 pa3) {
;   const s16x4 l0 = tr_read<BOFF + v_rd_off(D0, 0, 0)>(vb), h0 = tr_read<BOFF + v_rd_off(D0, 0, 1)>(vb), l1 = tr_read<BOFF + v_rd_off(D0, 1, 0)>(vb), h1 = tr_read<BOFF + v_rd_off(D0, 1, 1)>(vb);
;   const s16x4 l2 = tr_read<BOFF + v_rd_off(D0, 2, 0)>(vb), h2 = tr_read<BOFF + v_rd_off(D0, 2, 1)>(vb), l3 = tr_read<BOFF + v_rd_off(D0, 3, 0)>(vb), h3 = tr_read<BOFF + v_rd_off(D0, 3, 1)>(vb);
;   asm volatile("s_waitcnt lgkmcnt(0)" ::: "memory"); SBAR();
;     ...
;   od = __builtin_amdgcn_mfma_f32_32x32x16_bf16(pa0, PK(l0, h0), od, 0, 0, 0);
;   od = __builtin_amdgcn_mfma_f32_32x32x16_bf16(pa1, PK(l1, h1), od, 0, 0, 0);
;   od = __builtin_amdgcn_mfma_f32_32x32x16_bf16(pa2, PK(l2, h2), od, 0, 0, 0);
;   od = __builtin_amdgcn_mfma_f32_32x32x16_bf16(pa3, PK(l3, h3), od, 0, 0, 0);
;     ...
; }
; template <int BOFF> __device__ __forceinline__ void pv_i(f32x16* o, int vb, bf16x8 pa0, bf16x8 pa1, bf16x8 pa2, bf16x8 pa3) {
;   pv_one_i<0, BOFF>(o[0], vb, pa0, pa1, pa2, pa3); pv_one_i<1, BOFF>(o[1], vb, pa0, pa1, pa2, pa3); pv_one_i<2, BOFF>(o[2], vb, pa0, pa1, pa2, pa3); pv_one_i<3, BOFF>(o[3], vb, pa0, pa1, pa2, pa3);
; }
	v_mfma_f32_32x32x16_bf16 v[96:111], v[150:153], v[120:123], v[96:111]
	ds_read_b128 v[146:149], v191 offset:16384
	ds_read_b128 v[150:153], v191 offset:24576
	v_add_f32_e32 v64, v160, v64
	v_add_f32_e32 v180, v79, v64
	v_cvt_pk_bf16_f32 v64, v181, v183
	v_cvt_pk_bf16_f32 v65, v184, v185
	v_cvt_pk_bf16_f32 v66, v186, v187
	v_cvt_pk_bf16_f32 v67, v188, v189
	s_waitcnt lgkmcnt(1)
	v_mfma_f32_32x32x16_bf16 v[80:95], v[146:149], v[124:127], v[80:95]
	v_cvt_pk_bf16_f32 v68, v196, v197
	v_cvt_pk_bf16_f32 v69, v198, v199
	v_cvt_pk_bf16_f32 v70, v215, v216
	v_cvt_pk_bf16_f32 v71, v217, v218
	v_cvt_pk_bf16_f32 v72, v236, v237
	s_waitcnt lgkmcnt(0)
	v_mfma_f32_32x32x16_bf16 v[96:111], v[150:153], v[124:127], v[96:111]
	ds_read_b128 v[146:149], v192 offset:16384
	ds_read_b128 v[150:153], v192 offset:24576
	v_cvt_pk_bf16_f32 v73, v238, v239
	v_cvt_pk_bf16_f32 v74, v247, v248
	v_cvt_pk_bf16_f32 v75, v249, v252
	v_cvt_pk_bf16_f32 v76, v154, v155
	v_cvt_pk_bf16_f32 v77, v156, v157
	v_cvt_pk_bf16_f32 v78, v158, v159
	s_waitcnt lgkmcnt(1)
	v_mfma_f32_32x32x16_bf16 v[80:95], v[146:149], v[130:133], v[80:95]
	v_cvt_pk_bf16_f32 v79, v160, v79
	v_mov_b32_e32 v182, v180
	v_permlane32_swap_b32_e32 v64, v66
	v_permlane32_swap_b32_e32 v65, v67
	v_permlane32_swap_b32_e32 v68, v70
	s_waitcnt lgkmcnt(0)
	v_mfma_f32_32x32x16_bf16 v[96:111], v[150:153], v[130:133], v[96:111]
	ds_read_b128 v[146:149], v193 offset:16384
	ds_read_b128 v[150:153], v193 offset:24576
	ds_read_b64_tr_b16 v[184:185], v206 offset:0
	ds_read_b64_tr_b16 v[186:187], v206 offset:0x800
	ds_read_b64_tr_b16 v[216:217], v206 offset:0x1000
	ds_read_b64_tr_b16 v[218:219], v206 offset:0x1800
	ds_read_b64_tr_b16 v[220:221], v206 offset:0x2000
	ds_read_b64_tr_b16 v[222:223], v206 offset:0x2800
	ds_read_b64_tr_b16 v[224:225], v206 offset:0x3000
	ds_read_b64_tr_b16 v[226:227], v206 offset:0x3800
	v_permlane32_swap_b32_e32 v69, v71
	v_permlane32_swap_b32_e32 v72, v74
	v_permlane32_swap_b32_e32 v73, v75
	v_permlane32_swap_b32_e32 v76, v78
	v_permlane32_swap_b32_e32 v77, v79
	v_permlane32_swap_b32_e32 v180, v182
	s_waitcnt lgkmcnt(9)
	v_mfma_f32_32x32x16_bf16 v[80:95], v[146:149], v[134:137], v[80:95]
	s_waitcnt lgkmcnt(8)
	v_mfma_f32_32x32x16_bf16 v[96:111], v[150:153], v[134:137], v[96:111]
	v_add_co_u32_e32 v150, vcc, s25, v178
	s_nop 1
	v_addc_co_u32_e32 v151, vcc, -1, v179, vcc
	v_add_co_u32_e32 v154, vcc, s45, v178
	s_nop 1
	v_addc_co_u32_e32 v155, vcc, -1, v179, vcc
	global_load_dwordx4 v[146:149], v[150:151], off
	s_nop 0
	global_load_dwordx4 v[150:153], v[150:151], off offset:-512
	s_nop 0
	global_load_dwordx4 v[158:161], v[154:155], off
	s_nop 0
	global_load_dwordx4 v[154:157], v[154:155], off offset:-512
	s_waitcnt vmcnt(4)
	ds_write_b128 v211, v[162:165] offset:32768
	s_nop 0
	s_waitcnt lgkmcnt(7)
	v_mfma_f32_32x32x16_bf16 v[0:15], v[64:67], v[184:187], v[0:15]
	ds_read_b64_tr_b16 v[184:185], v206 offset:0x200
	ds_read_b64_tr_b16 v[186:187], v206 offset:0xa00
	s_waitcnt lgkmcnt(7)
	v_mfma_f32_32x32x16_bf16 v[0:15], v[68:71], v[216:219], v[0:15]
	ds_read_b64_tr_b16 v[216:217], v206 offset:0x1200
	ds_read_b64_tr_b16 v[218:219], v206 offset:0x1a00
	s_waitcnt lgkmcnt(7)
	v_mfma_f32_32x32x16_bf16 v[0:15], v[72:75], v[220:223], v[0:15]
	ds_read_b64_tr_b16 v[220:221], v206 offset:0x2200
	ds_read_b64_tr_b16 v[222:223], v206 offset:0x2a00
	s_waitcnt lgkmcnt(7)
	v_mfma_f32_32x32x16_bf16 v[0:15], v[76:79], v[224:227], v[0:15]
	ds_read_b64_tr_b16 v[224:225], v206 offset:0x3200
	ds_read_b64_tr_b16 v[226:227], v206 offset:0x3a00
	ds_write_b128 v212, v[174:177] offset:32768
	s_waitcnt lgkmcnt(7)
	v_mfma_f32_32x32x16_bf16 v[16:31], v[64:67], v[184:187], v[16:31]
	ds_read_b64_tr_b16 v[184:185], v206 offset:0x400
	ds_read_b64_tr_b16 v[186:187], v206 offset:0xc00
	s_waitcnt lgkmcnt(7)
	v_mfma_f32_32x32x16_bf16 v[16:31], v[68:71], v[216:219], v[16:31]
	ds_read_b64_tr_b16 v[216:217], v206 offset:0x1400
	ds_read_b64_tr_b16 v[218:219], v206 offset:0x1c00
	s_waitcnt lgkmcnt(7)
	v_mfma_f32_32x32x16_bf16 v[16:31], v[72:75], v[220:223], v[16:31]
	ds_read_b64_tr_b16 v[220:221], v206 offset:0x2400
	ds_read_b64_tr_b16 v[222:223], v206 offset:0x2c00
	s_waitcnt lgkmcnt(7)
	v_mfma_f32_32x32x16_bf16 v[16:31], v[76:79], v[224:227], v[16:31]
	ds_read_b64_tr_b16 v[224:225], v206 offset:0x3400
	ds_read_b64_tr_b16 v[226:227], v206 offset:0x3c00
	ds_write_b128 v213, v[166:169] offset:32768
	s_waitcnt lgkmcnt(7)
	v_mfma_f32_32x32x16_bf16 v[32:47], v[64:67], v[184:187], v[32:47]
	ds_read_b64_tr_b16 v[184:185], v206 offset:0x600
	ds_read_b64_tr_b16 v[186:187], v206 offset:0xe00
	s_waitcnt lgkmcnt(7)
	v_mfma_f32_32x32x16_bf16 v[32:47], v[68:71], v[216:219], v[32:47]
	ds_read_b64_tr_b16 v[216:217], v206 offset:0x1600
	ds_read_b64_tr_b16 v[218:219], v206 offset:0x1e00
	s_waitcnt lgkmcnt(7)
	v_mfma_f32_32x32x16_bf16 v[32:47], v[72:75], v[220:223], v[32:47]
	ds_read_b64_tr_b16 v[220:221], v206 offset:0x2600
	ds_read_b64_tr_b16 v[222:223], v206 offset:0x2e00
	s_waitcnt lgkmcnt(7)
	v_mfma_f32_32x32x16_bf16 v[32:47], v[76:79], v[224:227], v[32:47]
	ds_read_b64_tr_b16 v[224:225], v206 offset:0x3600
	ds_read_b64_tr_b16 v[226:227], v206 offset:0x3e00
	ds_write_b128 v214, v[170:173] offset:32768
	s_waitcnt lgkmcnt(7)
	v_mfma_f32_32x32x16_bf16 v[48:63], v[64:67], v[184:187], v[48:63]
	v_exp_f32_e32 v215, v90
	s_waitcnt vmcnt(4)
	v_exp_f32_e32 v184, v80
	v_exp_f32_e32 v185, v81
	v_exp_f32_e32 v186, v82
	v_exp_f32_e32 v187, v83
	v_exp_f32_e32 v188, v84
	s_waitcnt lgkmcnt(5)
	v_mfma_f32_32x32x16_bf16 v[48:63], v[68:71], v[216:219], v[48:63]
	v_exp_f32_e32 v219, v94
	v_exp_f32_e32 v189, v85
	v_exp_f32_e32 v196, v86
	v_exp_f32_e32 v197, v87
	v_exp_f32_e32 v198, v88
	v_exp_f32_e32 v199, v89
	v_exp_f32_e32 v216, v91
	s_waitcnt lgkmcnt(0)
	s_barrier
; template <int BOFF> __device__ __forceinline__ void qkt_i(f32x16& p0, f32x16& p1, const int (&kb)[4], const bf16x8* qr) {
;   p0 = f32x16{}; p1 = f32x16{};
; #pragma unroll
;   for (int d0 = 0; d0 < 8; ++d0) { const int off = BOFF + (d0 >> 2) * 128;
;     const bf16x8 b0 = LDSV(kb[d0 & 3] + off), b1 = LDSV(kb[d0 & 3] + off + 8192);
;     p0 = __builtin_amdgcn_mfma_f32_32x32x16_bf16(b0, qr[d0], p0, 0, 0, 0);
;     p1 = __builtin_amdgcn_mfma_f32_32x32x16_bf16(b1, qr[d0], p1, 0, 0, 0); }
; }
	ds_read_b128 v[64:67], v207 offset:32768
	ds_read_b128 v[80:83], v207 offset:40960
	ds_read_b128 v[162:165], v208 offset:32768
	ds_read_b128 v[166:169], v208 offset:40960
	v_mfma_f32_32x32x16_bf16 v[48:63], v[72:75], v[220:223], v[48:63]
	v_mfma_f32_32x32x16_bf16 v[48:63], v[76:79], v[224:227], v[48:63]
	v_exp_f32_e32 v220, v95
	v_exp_f32_e32 v217, v92
	v_exp_f32_e32 v218, v93
	v_exp_f32_e32 v170, v104
	v_exp_f32_e32 v171, v105
	v_exp_f32_e32 v172, v106
	v_exp_f32_e32 v173, v107
	v_exp_f32_e32 v174, v108
	v_exp_f32_e32 v175, v109
	v_exp_f32_e32 v176, v110
	v_exp_f32_e32 v111, v111
	s_waitcnt lgkmcnt(3)
	v_mfma_f32_32x32x16_bf16 v[64:79], v[64:67], v[142:145], 0
	v_exp_f32_e32 v236, v96
	v_add_f32_e32 v96, 0, v184
	v_add_f32_e32 v96, v185, v96
	v_add_f32_e32 v96, v186, v96
	s_waitcnt lgkmcnt(2)
	v_mfma_f32_32x32x16_bf16 v[80:95], v[80:83], v[142:145], 0
	v_add_f32_e32 v96, v187, v96
	v_add_f32_e32 v96, v188, v96
	v_add_f32_e32 v96, v189, v96
	s_waitcnt lgkmcnt(1)
	v_mfma_f32_32x32x16_bf16 v[64:79], v[162:165], v[138:141], v[64:79]
	v_add_f32_e32 v96, v196, v96
	v_add_f32_e32 v96, v197, v96
	v_add_f32_e32 v96, v198, v96
	s_waitcnt lgkmcnt(0)
	v_mfma_f32_32x32x16_bf16 v[80:95], v[166:169], v[138:141], v[80:95]
	ds_read_b128 v[162:165], v209 offset:32768
	ds_read_b128 v[166:169], v209 offset:40960
	v_add_f32_e32 v96, v199, v96
	v_add_f32_e32 v96, v215, v96
	v_add_f32_e32 v96, v216, v96
	v_add_f32_e32 v96, v217, v96
	v_exp_f32_e32 v237, v97
	s_waitcnt lgkmcnt(1)
	v_mfma_f32_32x32x16_bf16 v[64:79], v[162:165], v[112:115], v[64:79]
	v_add_f32_e32 v96, v218, v96
	v_exp_f32_e32 v238, v98
	v_add_f32_e32 v96, v219, v96
	v_exp_f32_e32 v239, v99
	s_waitcnt lgkmcnt(0)
	v_mfma_f32_32x32x16_bf16 v[80:95], v[166:169], v[112:115], v[80:95]
	ds_read_b128 v[162:165], v210 offset:32768
	ds_read_b128 v[166:169], v210 offset:40960
	v_add_f32_e32 v96, v220, v96
	v_exp_f32_e32 v247, v100
	v_add_f32_e32 v96, v236, v96
	v_exp_f32_e32 v248, v101
	s_waitcnt lgkmcnt(1)
	v_mfma_f32_32x32x16_bf16 v[64:79], v[162:165], v[116:119], v[64:79]
	v_add_f32_e32 v96, v237, v96
	v_exp_f32_e32 v249, v102
	v_add_f32_e32 v96, v238, v96
	v_exp_f32_e32 v252, v103
	s_waitcnt lgkmcnt(0)
	v_mfma_f32_32x32x16_bf16 v[80:95], v[166:169], v[116:119], v[80:95]
	ds_read_b128 v[162:165], v190 offset:32768
	ds_read_b128 v[166:169], v190 offset:40960
	v_add_f32_e32 v96, v239, v96
	v_add_f32_e32 v96, v247, v96
	v_add_f32_e32 v96, v248, v96
	v_add_f32_e32 v96, v249, v96
	v_add_f32_e32 v96, v252, v96
	v_add_f32_e32 v96, v170, v96
	s_waitcnt lgkmcnt(1)
	v_mfma_f32_32x32x16_bf16 v[64:79], v[162:165], v[120:123], v[64:79]
	v_add_f32_e32 v96, v171, v96
	v_add_f32_e32 v96, v172, v96
	v_add_f32_e32 v96, v173, v96
	v_add_f32_e32 v96, v174, v96
	v_add_f32_e32 v96, v175, v96
	s_waitcnt lgkmcnt(0)
	v_mfma_f32_32x32x16_bf16 v[80:95], v[166:169], v[120:123], v[80:95]
	ds_read_b128 v[162:165], v191 offset:32768
	ds_read_b128 v[166:169], v191 offset:40960
	v_add_f32_e32 v96, v176, v96
	v_add_f32_e32 v181, v111, v96
	v_mov_b32_e32 v183, v181
	s_nop 1
	v_permlane32_swap_b32_e32 v181, v183
	v_pk_add_f32 v[96:97], v[180:181], v[182:183]
	s_waitcnt lgkmcnt(1)
	v_mfma_f32_32x32x16_bf16 v[64:79], v[162:165], v[124:127], v[64:79]
	s_nop 0
	v_add_f32_e32 v96, v128, v96
	v_add_f32_e32 v128, v96, v97
	v_cvt_pk_bf16_f32 v96, v184, v185
	v_cvt_pk_bf16_f32 v97, v186, v187
	s_waitcnt lgkmcnt(0)
	v_mfma_f32_32x32x16_bf16 v[80:95], v[166:169], v[124:127], v[80:95]
	ds_read_b128 v[162:165], v192 offset:32768
	ds_read_b128 v[166:169], v192 offset:40960
	v_cvt_pk_bf16_f32 v98, v188, v189
	v_cvt_pk_bf16_f32 v99, v196, v197
	v_cvt_pk_bf16_f32 v100, v198, v199
	v_cvt_pk_bf16_f32 v101, v215, v216
	v_cvt_pk_bf16_f32 v102, v217, v218
	v_cvt_pk_bf16_f32 v103, v219, v220
	s_waitcnt lgkmcnt(1)
	v_mfma_f32_32x32x16_bf16 v[64:79], v[162:165], v[130:133], v[64:79]
	v_cvt_pk_bf16_f32 v104, v236, v237
	v_cvt_pk_bf16_f32 v105, v238, v239
	v_cvt_pk_bf16_f32 v106, v247, v248
	v_cvt_pk_bf16_f32 v107, v249, v252
	v_cvt_pk_bf16_f32 v108, v170, v171
	s_waitcnt lgkmcnt(0)
	v_mfma_f32_32x32x16_bf16 v[80:95], v[166:169], v[130:133], v[80:95]
	ds_read_b128 v[162:165], v193 offset:32768
	ds_read_b128 v[166:169], v193 offset:40960
	ds_read_b64_tr_b16 v[180:181], v206 offset:0x4000
	ds_read_b64_tr_b16 v[182:183], v206 offset:0x4800
	ds_read_b64_tr_b16 v[184:185], v206 offset:0x5000
	ds_read_b64_tr_b16 v[186:187], v206 offset:0x5800
	ds_read_b64_tr_b16 v[216:217], v206 offset:0x6000
	ds_read_b64_tr_b16 v[218:219], v206 offset:0x6800
	ds_read_b64_tr_b16 v[220:221], v206 offset:0x7000
	ds_read_b64_tr_b16 v[222:223], v206 offset:0x7800
	v_cvt_pk_bf16_f32 v109, v172, v173
	v_cvt_pk_bf16_f32 v110, v174, v175
	v_cvt_pk_bf16_f32 v111, v176, v111
	s_nop 0
	v_permlane32_swap_b32_e32 v96, v98
	v_permlane32_swap_b32_e32 v97, v99
	s_waitcnt lgkmcnt(9)
	v_mfma_f32_32x32x16_bf16 v[64:79], v[162:165], v[134:137], v[64:79]
	v_permlane32_swap_b32_e32 v100, v102
	v_permlane32_swap_b32_e32 v101, v103
	v_permlane32_swap_b32_e32 v104, v106
	v_permlane32_swap_b32_e32 v105, v107
	v_permlane32_swap_b32_e32 v108, v110
	s_waitcnt lgkmcnt(8)
	v_mfma_f32_32x32x16_bf16 v[80:95], v[166:169], v[134:137], v[80:95]
	v_permlane32_swap_b32_e32 v109, v111
	v_add_co_u32_e32 v166, vcc, s52, v178
	s_nop 1
	v_addc_co_u32_e32 v167, vcc, -1, v179, vcc
	v_add_co_u32_e32 v170, vcc, s53, v178
	s_nop 1
	v_addc_co_u32_e32 v171, vcc, -1, v179, vcc
	global_load_dwordx4 v[162:165], v[166:167], off
	s_nop 0
	global_load_dwordx4 v[166:169], v[166:167], off offset:-512
	s_nop 0
	global_load_dwordx4 v[174:177], v[170:171], off
	s_nop 0
	global_load_dwordx4 v[170:173], v[170:171], off offset:-512
	s_waitcnt vmcnt(4)
; #define SBAR() __builtin_amdgcn_sched_barrier(0)
; template <int D0, int BOFF> __device__ __forceinline__ void pv_one_i(f32x16& od, int vb, bf16x8 pa0, bf16x8 pa1, bf16x8 pa2, bf16x8 pa3) {
;   const s16x4 l0 = tr_read<BOFF + v_rd_off(D0, 0, 0)>(vb), h0 = tr_read<BOFF + v_rd_off(D0, 0, 1)>(vb), l1 = tr_read<BOFF + v_rd_off(D0, 1, 0)>(vb), h1 = tr_read<BOFF + v_rd_off(D0, 1, 1)>(vb);
;   const s16x4 l2 = tr_read<BOFF + v_rd_off(D0, 2, 0)>(vb), h2 = tr_read<BOFF + v_rd_off(D0, 2, 1)>(vb), l3 = tr_read<BOFF + v_rd_off(D0, 3, 0)>(vb), h3 = tr_read<BOFF + v_rd_off(D0, 3, 1)>(vb);
;   asm volatile("s_waitcnt lgkmcnt(0)" ::: "memory"); SBAR();
;     ...
;   od = __builtin_amdgcn_mfma_f32_32x32x16_bf16(pa0, PK(l0, h0), od, 0, 0, 0);
;   od = __builtin_amdgcn_mfma_f32_32x32x16_bf16(pa1, PK(l1, h1), od, 0, 0, 0);
;   od = __builtin_amdgcn_mfma_f32_32x32x16_bf16(pa2, PK(l2, h2), od, 0, 0, 0);
;   od = __builtin_amdgcn_mfma_f32_32x32x16_bf16(pa3, PK(l3, h3), od, 0, 0, 0);
;     ...
; }
; template <int BOFF> __device__ __forceinline__ void pv_i(f32x16* o, int vb, bf16x8 pa0, bf16x8 pa1, bf16x8 pa2, bf16x8 pa3) {
;   pv_one_i<0, BOFF>(o[0], vb, pa0, pa1, pa2, pa3); pv_one_i<1, BOFF>(o[1], vb, pa0, pa1, pa2, pa3); pv_one_i<2, BOFF>(o[2], vb, pa0, pa1, pa2, pa3); pv_one_i<3, BOFF>(o[3], vb, pa0, pa1, pa2, pa3);
; }
	ds_write_b128 v211, v[146:149]
	s_nop 0
	s_waitcnt lgkmcnt(7)
	v_mfma_f32_32x32x16_bf16 v[0:15], v[96:99], v[180:183], v[0:15]
	ds_read_b64_tr_b16 v[180:181], v206 offset:0x4200
	ds_read_b64_tr_b16 v[182:183], v206 offset:0x4a00
	s_waitcnt lgkmcnt(7)
	v_mfma_f32_32x32x16_bf16 v[0:15], v[100:103], v[184:187], v[0:15]
	ds_read_b64_tr_b16 v[184:185], v206 offset:0x5200
	ds_read_b64_tr_b16 v[186:187], v206 offset:0x5a00
	s_waitcnt lgkmcnt(7)
	v_mfma_f32_32x32x16_bf16 v[0:15], v[104:107], v[216:219], v[0:15]
	ds_read_b64_tr_b16 v[216:217], v206 offset:0x6200
	ds_read_b64_tr_b16 v[218:219], v206 offset:0x6a00
	s_waitcnt lgkmcnt(7)
	v_mfma_f32_32x32x16_bf16 v[0:15], v[108:111], v[220:223], v[0:15]
	ds_read_b64_tr_b16 v[220:221], v206 offset:0x7200
	ds_read_b64_tr_b16 v[222:223], v206 offset:0x7a00
	ds_write_b128 v212, v[158:161]
	s_waitcnt lgkmcnt(7)
	v_mfma_f32_32x32x16_bf16 v[16:31], v[96:99], v[180:183], v[16:31]
	ds_read_b64_tr_b16 v[180:181], v206 offset:0x4400
	ds_read_b64_tr_b16 v[182:183], v206 offset:0x4c00
	s_waitcnt lgkmcnt(7)
	v_mfma_f32_32x32x16_bf16 v[16:31], v[100:103], v[184:187], v[16:31]
	ds_read_b64_tr_b16 v[184:185], v206 offset:0x5400
	ds_read_b64_tr_b16 v[186:187], v206 offset:0x5c00
	s_waitcnt lgkmcnt(7)
	v_mfma_f32_32x32x16_bf16 v[16:31], v[104:107], v[216:219], v[16:31]
	ds_read_b64_tr_b16 v[216:217], v206 offset:0x6400
	ds_read_b64_tr_b16 v[218:219], v206 offset:0x6c00
	s_waitcnt lgkmcnt(7)
	v_mfma_f32_32x32x16_bf16 v[16:31], v[108:111], v[220:223], v[16:31]
	ds_read_b64_tr_b16 v[220:221], v206 offset:0x7400
	ds_read_b64_tr_b16 v[222:223], v206 offset:0x7c00
	ds_write_b128 v213, v[150:153]
	s_waitcnt lgkmcnt(7)
	v_mfma_f32_32x32x16_bf16 v[32:47], v[96:99], v[180:183], v[32:47]
	ds_read_b64_tr_b16 v[180:181], v206 offset:0x4600
	ds_read_b64_tr_b16 v[182:183], v206 offset:0x4e00
	s_waitcnt lgkmcnt(7)
	v_mfma_f32_32x32x16_bf16 v[32:47], v[100:103], v[184:187], v[32:47]
	ds_read_b64_tr_b16 v[184:185], v206 offset:0x5600
	ds_read_b64_tr_b16 v[186:187], v206 offset:0x5e00
	s_waitcnt lgkmcnt(7)
	v_mfma_f32_32x32x16_bf16 v[32:47], v[104:107], v[216:219], v[32:47]
	ds_read_b64_tr_b16 v[216:217], v206 offset:0x6600
	ds_read_b64_tr_b16 v[218:219], v206 offset:0x6e00
	s_waitcnt lgkmcnt(7)
	v_mfma_f32_32x32x16_bf16 v[32:47], v[108:111], v[220:223], v[32:47]
	ds_read_b64_tr_b16 v[220:221], v206 offset:0x7600
	ds_read_b64_tr_b16 v[222:223], v206 offset:0x7e00
	ds_write_b128 v214, v[154:157]
	s_waitcnt lgkmcnt(7)
	v_mfma_f32_32x32x16_bf16 v[48:63], v[96:99], v[180:183], v[48:63]
	s_waitcnt vmcnt(4)
	v_exp_f32_e32 v180, v64
	v_exp_f32_e32 v181, v65
	v_exp_f32_e32 v182, v66
	v_exp_f32_e32 v183, v67
	v_exp_f32_e32 v188, v72
	v_exp_f32_e32 v189, v73
	s_waitcnt lgkmcnt(5)
	v_mfma_f32_32x32x16_bf16 v[48:63], v[100:103], v[184:187], v[48:63]
	v_exp_f32_e32 v184, v68
	v_exp_f32_e32 v185, v69
	v_exp_f32_e32 v186, v70
	v_exp_f32_e32 v187, v71
	v_exp_f32_e32 v196, v74
	v_exp_f32_e32 v197, v75
	v_exp_f32_e32 v198, v76
	s_waitcnt lgkmcnt(0)
	s_barrier
	ds_read_b128 v[64:67], v207
	ds_read_b128 v[68:71], v207 offset:8192
	ds_read_b128 v[146:149], v208
	ds_read_b128 v[150:153], v208 offset:8192
	v_mfma_f32_32x32x16_bf16 v[48:63], v[104:107], v[216:219], v[48:63]
	v_mfma_f32_32x32x16_bf16 v[48:63], v[108:111], v[220:223], v[48:63]
	v_exp_f32_e32 v199, v77
	v_exp_f32_e32 v216, v78
	v_exp_f32_e32 v217, v79
	v_exp_f32_e32 v154, v88
	v_exp_f32_e32 v155, v89
	v_exp_f32_e32 v156, v90
	v_exp_f32_e32 v157, v91
	v_exp_f32_e32 v158, v92
	v_exp_f32_e32 v159, v93
	v_exp_f32_e32 v160, v94
	v_exp_f32_e32 v95, v95
	s_waitcnt lgkmcnt(3)
	v_mfma_f32_32x32x16_bf16 v[96:111], v[64:67], v[142:145], 0
	v_exp_f32_e32 v236, v80
	v_add_f32_e32 v80, 0, v180
	v_add_f32_e32 v80, v181, v80
	v_add_f32_e32 v80, v182, v80
	s_waitcnt lgkmcnt(2)
	v_mfma_f32_32x32x16_bf16 v[64:79], v[68:71], v[142:145], 0
	v_add_f32_e32 v80, v183, v80
	v_add_f32_e32 v80, v184, v80
	v_add_f32_e32 v80, v185, v80
	s_waitcnt lgkmcnt(1)
	v_mfma_f32_32x32x16_bf16 v[96:111], v[146:149], v[138:141], v[96:111]
	v_add_f32_e32 v80, v186, v80
	v_add_f32_e32 v80, v187, v80
	v_add_f32_e32 v80, v188, v80
	s_waitcnt lgkmcnt(0)
	v_mfma_f32_32x32x16_bf16 v[64:79], v[150:153], v[138:141], v[64:79]
	ds_read_b128 v[146:149], v209
	ds_read_b128 v[150:153], v209 offset:8192
	v_add_f32_e32 v80, v189, v80
	v_add_f32_e32 v80, v196, v80
	v_add_f32_e32 v80, v197, v80
	v_add_f32_e32 v80, v198, v80
	v_exp_f32_e32 v237, v81
	s_waitcnt lgkmcnt(1)
	v_mfma_f32_32x32x16_bf16 v[96:111], v[146:149], v[112:115], v[96:111]
	v_add_f32_e32 v80, v199, v80
	v_exp_f32_e32 v238, v82
	v_add_f32_e32 v80, v216, v80
	v_exp_f32_e32 v239, v83
	s_waitcnt lgkmcnt(0)
	v_mfma_f32_32x32x16_bf16 v[64:79], v[150:153], v[112:115], v[64:79]
	ds_read_b128 v[146:149], v210
	ds_read_b128 v[150:153], v210 offset:8192
	v_add_f32_e32 v80, v217, v80
	v_exp_f32_e32 v247, v84
	v_add_f32_e32 v80, v236, v80
	v_exp_f32_e32 v248, v85
	s_waitcnt lgkmcnt(1)
	v_mfma_f32_32x32x16_bf16 v[96:111], v[146:149], v[116:119], v[96:111]
	v_add_f32_e32 v80, v237, v80
	v_exp_f32_e32 v249, v86
	v_add_f32_e32 v80, v238, v80
	v_exp_f32_e32 v252, v87
	s_waitcnt lgkmcnt(0)
	v_mfma_f32_32x32x16_bf16 v[64:79], v[150:153], v[116:119], v[64:79]
	ds_read_b128 v[146:149], v190 offset:0
	ds_read_b128 v[150:153], v190 offset:8192
	v_add_f32_e32 v80, v239, v80
	v_add_f32_e32 v80, v247, v80
	v_add_f32_e32 v80, v248, v80
	v_add_f32_e32 v80, v249, v80
	v_add_f32_e32 v80, v252, v80
	v_add_f32_e32 v80, v154, v80
	s_waitcnt lgkmcnt(1)
	v_mfma_f32_32x32x16_bf16 v[96:111], v[146:149], v[120:123], v[96:111]
	v_add_f32_e32 v80, v155, v80
	v_add_f32_e32 v80, v156, v80
	v_add_f32_e32 v80, v157, v80
	v_add_f32_e32 v80, v158, v80
	v_add_f32_e32 v80, v159, v80
	s_waitcnt lgkmcnt(0)
; #define SLOAD(i, k0) do { sr_[i].vs0 = ld8(&Vh[(long)((k0) + sr) * LDK + sc]); sr_[i].vs1 = ld8(&Vh[(long)((k0) + 32 + sr) * LDK + sc]); \
;     sr_[i].ks0 = ld8(&Kh[(long)((k0) + sr) * LDK + sc]); sr_[i].ks1 = ld8(&Kh[(long)((k0) + 32 + sr) * LDK + sc]); } while (0)
; #define SWAIT() asm volatile("s_waitcnt vmcnt(4)" ::: "memory")
; #define SWRITE_I(B, i) do { LDSV(wv0 + (B) * 16384) = sr_[i].vs0; LDSV(wv1 + (B) * 16384) = sr_[i].vs1; LDSV(wk0 + (B) * 16384) = sr_[i].ks0; LDSV(wk1 + (B) * 16384) = sr_[i].ks1; } while (0)
; #define NOP_() do { } while (0)
; template <bool PARTIAL, bool FIXED> ...
;     ...
;   for (; j + 6 < NT; j += 6) {
;     HALF_B(1, 0, SLOAD(1, (j + 2) * KVBLK), do { SWAIT(); SWRITE_I(2, 0); } while (0));
;     HALF_A(2, 1, NOP_(), SLOAD(0, (j + 3) * KVBLK), do { SWAIT(); SWRITE_I(0, 1); } while (0));
;     HALF_B(0, 2, SLOAD(1, (j + 4) * KVBLK), do { SWAIT(); SWRITE_I(1, 0); } while (0));
;     HALF_A(1, 0, NOP_(), SLOAD(0, (j + 5) * KVBLK), do { SWAIT(); SWRITE_I(2, 1); } while (0));
;     HALF_B(2, 1, SLOAD(1, (j + 6) * KVBLK), do { SWAIT(); SWRITE_I(0, 0); } while (0));
;     HALF_A(0, 2, NOP_(), SLOAD(0, (j + 7) * KVBLK), do { SWAIT(); SWRITE_I(1, 1); } while (0));
;   }
	v_mfma_f32_32x32x16_bf16 v[64:79], v[150:153], v[120:123], v[64:79]
	ds_read_b128 v[146:149], v191 offset:0
	ds_read_b128 v[150:153], v191 offset:8192
	v_add_f32_e32 v80, v160, v80
	v_add_f32_e32 v80, v95, v80
	v_mov_b32_e32 v81, v80
	s_nop 1
	v_permlane32_swap_b32_e32 v80, v81
	v_add_f32_e32 v80, v80, v81
	s_waitcnt lgkmcnt(1)
	v_mfma_f32_32x32x16_bf16 v[96:111], v[146:149], v[124:127], v[96:111]
	v_add_f32_e32 v215, v128, v80
	v_cvt_pk_bf16_f32 v80, v180, v181
	v_cvt_pk_bf16_f32 v81, v182, v183
	v_cvt_pk_bf16_f32 v82, v184, v185
	v_cvt_pk_bf16_f32 v83, v186, v187
	s_waitcnt lgkmcnt(0)
	v_mfma_f32_32x32x16_bf16 v[64:79], v[150:153], v[124:127], v[64:79]
	ds_read_b128 v[146:149], v192 offset:0
	ds_read_b128 v[150:153], v192 offset:8192
	v_cvt_pk_bf16_f32 v84, v188, v189
	v_cvt_pk_bf16_f32 v85, v196, v197
	v_cvt_pk_bf16_f32 v86, v198, v199
	v_cvt_pk_bf16_f32 v87, v216, v217
	v_cvt_pk_bf16_f32 v88, v236, v237
	v_cvt_pk_bf16_f32 v89, v238, v239
	s_waitcnt lgkmcnt(1)
	v_mfma_f32_32x32x16_bf16 v[96:111], v[146:149], v[130:133], v[96:111]
	v_cvt_pk_bf16_f32 v90, v247, v248
	v_cvt_pk_bf16_f32 v91, v249, v252
	v_cvt_pk_bf16_f32 v92, v154, v155
	v_cvt_pk_bf16_f32 v93, v156, v157
	v_cvt_pk_bf16_f32 v94, v158, v159
	s_waitcnt lgkmcnt(0)
	v_mfma_f32_32x32x16_bf16 v[64:79], v[150:153], v[130:133], v[64:79]
	ds_read_b128 v[146:149], v193 offset:0
	ds_read_b128 v[150:153], v193 offset:8192
	ds_read_b64_tr_b16 v[180:181], v206 offset:0x8000
	ds_read_b64_tr_b16 v[182:183], v206 offset:0x8800
	ds_read_b64_tr_b16 v[184:185], v206 offset:0x9000
	ds_read_b64_tr_b16 v[186:187], v206 offset:0x9800
	ds_read_b64_tr_b16 v[216:217], v206 offset:0xa000
	ds_read_b64_tr_b16 v[218:219], v206 offset:0xa800
	ds_read_b64_tr_b16 v[220:221], v206 offset:0xb000
	ds_read_b64_tr_b16 v[222:223], v206 offset:0xb800
	v_cvt_pk_bf16_f32 v95, v160, v95
	s_nop 0
	v_permlane32_swap_b32_e32 v80, v82
	v_permlane32_swap_b32_e32 v81, v83
	v_permlane32_swap_b32_e32 v84, v86
	v_permlane32_swap_b32_e32 v85, v87
	s_waitcnt lgkmcnt(9)
	v_mfma_f32_32x32x16_bf16 v[96:111], v[146:149], v[134:137], v[96:111]
	v_permlane32_swap_b32_e32 v88, v90
	v_permlane32_swap_b32_e32 v89, v91
	v_permlane32_swap_b32_e32 v92, v94
	v_permlane32_swap_b32_e32 v93, v95
	s_waitcnt lgkmcnt(8)
	v_mfma_f32_32x32x16_bf16 v[64:79], v[150:153], v[134:137], v[64:79]
	v_add_co_u32_e32 v150, vcc, s58, v178
	s_nop 1
	v_addc_co_u32_e32 v151, vcc, -1, v179, vcc
	global_load_dwordx4 v[146:149], v[150:151], off
	global_load_dwordx4 v[154:157], v[150:151], off offset:-512
	s_nop 0
	global_load_dwordx4 v[150:153], v[178:179], off
	global_load_dwordx4 v[158:161], v[178:179], off offset:-512
	s_waitcnt vmcnt(4)
	ds_write_b128 v211, v[162:165] offset:16384
	s_nop 0
	s_waitcnt lgkmcnt(7)
	v_mfma_f32_32x32x16_bf16 v[0:15], v[80:83], v[180:183], v[0:15]
	ds_read_b64_tr_b16 v[180:181], v206 offset:0x8200
	ds_read_b64_tr_b16 v[182:183], v206 offset:0x8a00
	s_waitcnt lgkmcnt(7)
	v_mfma_f32_32x32x16_bf16 v[0:15], v[84:87], v[184:187], v[0:15]
	ds_read_b64_tr_b16 v[184:185], v206 offset:0x9200
	ds_read_b64_tr_b16 v[186:187], v206 offset:0x9a00
	s_waitcnt lgkmcnt(7)
	v_mfma_f32_32x32x16_bf16 v[0:15], v[88:91], v[216:219], v[0:15]
	ds_read_b64_tr_b16 v[216:217], v206 offset:0xa200
	ds_read_b64_tr_b16 v[218:219], v206 offset:0xaa00
	s_waitcnt lgkmcnt(7)
	v_mfma_f32_32x32x16_bf16 v[0:15], v[92:95], v[220:223], v[0:15]
	ds_read_b64_tr_b16 v[220:221], v206 offset:0xb200
	ds_read_b64_tr_b16 v[222:223], v206 offset:0xba00
	ds_write_b128 v212, v[174:177] offset:16384
	s_waitcnt lgkmcnt(7)
	v_mfma_f32_32x32x16_bf16 v[16:31], v[80:83], v[180:183], v[16:31]
	ds_read_b64_tr_b16 v[180:181], v206 offset:0x8400
	ds_read_b64_tr_b16 v[182:183], v206 offset:0x8c00
	s_waitcnt lgkmcnt(7)
	v_mfma_f32_32x32x16_bf16 v[16:31], v[84:87], v[184:187], v[16:31]
	ds_read_b64_tr_b16 v[184:185], v206 offset:0x9400
	ds_read_b64_tr_b16 v[186:187], v206 offset:0x9c00
	s_waitcnt lgkmcnt(7)
	v_mfma_f32_32x32x16_bf16 v[16:31], v[88:91], v[216:219], v[16:31]
	ds_read_b64_tr_b16 v[216:217], v206 offset:0xa400
	ds_read_b64_tr_b16 v[218:219], v206 offset:0xac00
	s_waitcnt lgkmcnt(7)
	v_mfma_f32_32x32x16_bf16 v[16:31], v[92:95], v[220:223], v[16:31]
	ds_read_b64_tr_b16 v[220:221], v206 offset:0xb400
	ds_read_b64_tr_b16 v[222:223], v206 offset:0xbc00
	ds_write_b128 v213, v[166:169] offset:16384
	s_waitcnt lgkmcnt(7)
	v_mfma_f32_32x32x16_bf16 v[32:47], v[80:83], v[180:183], v[32:47]
	ds_read_b64_tr_b16 v[180:181], v206 offset:0x8600
	ds_read_b64_tr_b16 v[182:183], v206 offset:0x8e00
	s_waitcnt lgkmcnt(7)
	v_mfma_f32_32x32x16_bf16 v[32:47], v[84:87], v[184:187], v[32:47]
	ds_read_b64_tr_b16 v[184:185], v206 offset:0x9600
	ds_read_b64_tr_b16 v[186:187], v206 offset:0x9e00
	s_waitcnt lgkmcnt(7)
	v_mfma_f32_32x32x16_bf16 v[32:47], v[88:91], v[216:219], v[32:47]
	ds_read_b64_tr_b16 v[216:217], v206 offset:0xa600
	ds_read_b64_tr_b16 v[218:219], v206 offset:0xae00
	s_waitcnt lgkmcnt(7)
	v_mfma_f32_32x32x16_bf16 v[32:47], v[92:95], v[220:223], v[32:47]
	ds_read_b64_tr_b16 v[220:221], v206 offset:0xb600
	ds_read_b64_tr_b16 v[222:223], v206 offset:0xbe00
	ds_write_b128 v214, v[170:173] offset:16384
	s_waitcnt lgkmcnt(7)
	v_mfma_f32_32x32x16_bf16 v[48:63], v[80:83], v[180:183], v[48:63]
	v_exp_f32_e32 v229, v96
	v_exp_f32_e32 v243, v97
	v_exp_f32_e32 v244, v98
	v_exp_f32_e32 v246, v99
	v_exp_f32_e32 v242, v100
	v_exp_f32_e32 v245, v101
	v_exp_f32_e32 v227, v102
	s_waitcnt lgkmcnt(5)
	v_mfma_f32_32x32x16_bf16 v[48:63], v[84:87], v[184:187], v[48:63]
	v_exp_f32_e32 v228, v103
	v_exp_f32_e32 v226, v105
	v_exp_f32_e32 v224, v106
	v_exp_f32_e32 v225, v107
	s_waitcnt vmcnt(4)
	s_add_i32 s28, s28, 6
	v_lshl_add_u64 v[178:179], v[178:179], 0, s[60:61]
	s_waitcnt lgkmcnt(3)
	v_mfma_f32_32x32x16_bf16 v[48:63], v[88:91], v[216:219], v[48:63]
	v_exp_f32_e32 v219, v110
	s_cmpk_lt_u32 s28, 0x75
	s_waitcnt lgkmcnt(1)
	v_mfma_f32_32x32x16_bf16 v[48:63], v[92:95], v[220:223], v[48:63]
	v_exp_f32_e32 v223, v104
	v_exp_f32_e32 v220, v108
	v_exp_f32_e32 v222, v109
	v_exp_f32_e32 v221, v111
	s_cbranch_scc1 .LBB0_352
; #define SWRITE_I(B, i) do { LDSV(wv0 + (B) * 16384) = sr_[i].vs0; LDSV(wv1 + (B) * 16384) = sr_[i].vs1; LDSV(wk0 + (B) * 16384) = sr_[i].ks0; LDSV(wk1 + (B) * 16384) = sr_[i].ks1; } while (0)
; #define NOP_() do { } while (0)
; template <bool PARTIAL, bool FIXED> ...
;     ...
;   if constexpr (!PARTIAL) { const int i1 = tid & 255;
;     warm0 = *(const unsigned*)(Qb_n + (long)(tid >> 1) * LDQ + (tid & 1) * 64);
;     warm1 = *(const unsigned*)((tid < 256 ? Kh_n : Vh_n) + (long)(i1 >> 1) * LDK + (i1 & 1) * 64); }
;   HALF_B(1, 0, NOP_(), SWRITE_I(2, 0));
	v_mov_b32_e32 v252, 0x7fc00000
	v_readlane_b32 s8, v255, 42
	v_readlane_b32 s9, v255, 43
	s_add_u32 s2, s8, s6
	s_addc_u32 s3, s9, s7
	s_lshl_b32 s4, s65, 1
	s_add_u32 s2, s2, s4
	s_addc_u32 s3, s3, 0
	v_ashrrev_i32_e32 v82, 1, v195
	v_mov_b64_e32 v[80:81], s[2:3]
	v_mad_i64_i32 v[80:81], s[2:3], v82, s17, v[80:81]
	v_lshlrev_b32_e32 v82, 7, v195
	v_and_b32_e32 v128, 0x80, v82
	v_lshl_add_u64 v[80:81], v[80:81], 0, v[128:129]
	s_add_u32 s4, s8, s64
	global_load_dword v216, v[80:81], off
	v_cmp_gt_i32_e32 vcc, s14, v195
	v_mov_b32_e32 v80, 0xa00
	v_mov_b32_e32 v81, 0x800
	s_addc_u32 s5, s9, s57
	v_cndmask_b32_e32 v80, v80, v81, vcc
	v_mov_b32_e32 v81, v129
	v_bfe_u32 v82, v195, 1, 7
	v_lshl_add_u64 v[80:81], s[4:5], 0, v[80:81]
	s_lshl_b32 s46, s56, 1
	v_mul_u32_u24_e32 v82, 0x600, v82
	v_lshl_add_u64 v[80:81], v[80:81], 0, s[46:47]
	v_lshlrev_b32_e32 v82, 1, v82
	v_mov_b32_e32 v83, v129
	v_lshl_add_u64 v[80:81], v[80:81], 0, v[82:83]
	v_lshl_add_u64 v[80:81], v[80:81], 0, v[128:129]
	global_load_dword v217, v[80:81], off
	v_and_b32_e32 v247, 0x3fffffc0, v195
	s_waitcnt lgkmcnt(0)
	s_barrier
	ds_read_b128 v[80:83], v207 offset:16384
	ds_read_b128 v[96:99], v207 offset:24576
	ds_read_b128 v[100:103], v208 offset:16384
	ds_read_b128 v[170:173], v208 offset:24576
	v_exp_f32_e32 v104, v68
	v_exp_f32_e32 v105, v69
	s_waitcnt lgkmcnt(3)
	v_mfma_f32_32x32x16_bf16 v[80:95], v[80:83], v[142:145], 0
	v_exp_f32_e32 v106, v70
	v_exp_f32_e32 v107, v71
	v_exp_f32_e32 v108, v72
	v_exp_f32_e32 v109, v73
	v_exp_f32_e32 v110, v74
	v_exp_f32_e32 v111, v75
	v_exp_f32_e32 v196, v76
	s_waitcnt lgkmcnt(1)
	v_mfma_f32_32x32x16_bf16 v[80:95], v[100:103], v[138:141], v[80:95]
	ds_read_b128 v[100:103], v209 offset:16384
	ds_read_b128 v[162:165], v209 offset:24576
	v_exp_f32_e32 v197, v77
	v_exp_f32_e32 v198, v78
	v_exp_f32_e32 v79, v79
	s_waitcnt lgkmcnt(1)
	v_mfma_f32_32x32x16_bf16 v[80:95], v[100:103], v[112:115], v[80:95]
	ds_read_b128 v[100:103], v210 offset:16384
	ds_read_b128 v[166:169], v210 offset:24576
	s_waitcnt lgkmcnt(1)
	v_mfma_f32_32x32x16_bf16 v[80:95], v[100:103], v[116:119], v[80:95]
	ds_read_b128 v[100:103], v190 offset:16384
	ds_read_b128 v[174:177], v190 offset:24576
	s_waitcnt lgkmcnt(1)
	v_mfma_f32_32x32x16_bf16 v[80:95], v[100:103], v[120:123], v[80:95]
	ds_read_b128 v[100:103], v191 offset:16384
	ds_read_b128 v[178:181], v191 offset:24576
	s_waitcnt lgkmcnt(1)
	v_mfma_f32_32x32x16_bf16 v[80:95], v[100:103], v[124:127], v[80:95]
	ds_read_b128 v[100:103], v192 offset:16384
	ds_read_b128 v[182:185], v192 offset:24576
	s_waitcnt lgkmcnt(1)
	v_mfma_f32_32x32x16_bf16 v[80:95], v[100:103], v[130:133], v[80:95]
	ds_read_b128 v[100:103], v193 offset:16384
	ds_read_b128 v[186:189], v193 offset:24576
	s_waitcnt lgkmcnt(1)
	v_mfma_f32_32x32x16_bf16 v[80:95], v[100:103], v[134:137], v[80:95]
	v_exp_f32_e32 v100, v64
	v_add_f32_e32 v64, 0, v229
	v_add_f32_e32 v64, v243, v64
	v_add_f32_e32 v64, v244, v64
	v_add_f32_e32 v64, v246, v64
	v_add_f32_e32 v64, v242, v64
	v_add_f32_e32 v64, v245, v64
	v_add_f32_e32 v64, v227, v64
	v_add_f32_e32 v64, v228, v64
	v_add_f32_e32 v64, v223, v64
	v_add_f32_e32 v64, v226, v64
	v_add_f32_e32 v64, v224, v64
	v_add_f32_e32 v64, v225, v64
	v_add_f32_e32 v64, v220, v64
	v_exp_f32_e32 v101, v65
	v_add_f32_e32 v64, v222, v64
	v_exp_f32_e32 v102, v66
	v_add_f32_e32 v64, v219, v64
	v_exp_f32_e32 v103, v67
	v_add_f32_e32 v64, v221, v64
	v_add_f32_e32 v64, v100, v64
	v_add_f32_e32 v64, v101, v64
	v_add_f32_e32 v64, v102, v64
	v_add_f32_e32 v64, v103, v64
	v_add_f32_e32 v64, v104, v64
	v_add_f32_e32 v64, v105, v64
	v_add_f32_e32 v64, v106, v64
	v_add_f32_e32 v64, v107, v64
	v_add_f32_e32 v64, v108, v64
	v_add_f32_e32 v64, v109, v64
	v_add_f32_e32 v64, v110, v64
	v_add_f32_e32 v64, v111, v64
	v_add_f32_e32 v64, v196, v64
	v_add_f32_e32 v64, v197, v64
	v_add_f32_e32 v64, v198, v64
	v_add_f32_e32 v128, v79, v64
	v_mov_b32_e32 v218, v128
	s_nop 1
	v_permlane32_swap_b32_e32 v128, v218
	v_cvt_pk_bf16_f32 v64, v229, v243
	v_cvt_pk_bf16_f32 v65, v244, v246
	v_cvt_pk_bf16_f32 v66, v242, v245
	v_cvt_pk_bf16_f32 v67, v227, v228
	v_cvt_pk_bf16_f32 v68, v223, v226
	v_cvt_pk_bf16_f32 v69, v224, v225
	v_cvt_pk_bf16_f32 v70, v220, v222
	v_cvt_pk_bf16_f32 v71, v219, v221
	v_cvt_pk_bf16_f32 v72, v100, v101
	v_cvt_pk_bf16_f32 v73, v102, v103
	v_cvt_pk_bf16_f32 v74, v104, v105
	v_cvt_pk_bf16_f32 v75, v106, v107
	v_cvt_pk_bf16_f32 v76, v108, v109
	v_cvt_pk_bf16_f32 v77, v110, v111
	v_cvt_pk_bf16_f32 v78, v196, v197
	v_cvt_pk_bf16_f32 v79, v198, v79
	s_nop 0
	v_permlane32_swap_b32_e32 v64, v66
	v_permlane32_swap_b32_e32 v65, v67
	v_permlane32_swap_b32_e32 v68, v70
	v_permlane32_swap_b32_e32 v69, v71
	v_permlane32_swap_b32_e32 v72, v74
	v_permlane32_swap_b32_e32 v73, v75
	v_permlane32_swap_b32_e32 v76, v78
	v_permlane32_swap_b32_e32 v77, v79
	ds_read_b64_tr_b16 v[100:101], v206 offset:0
	ds_read_b64_tr_b16 v[102:103], v206 offset:0x800
	ds_read_b64_tr_b16 v[104:105], v206 offset:0x1000
	ds_read_b64_tr_b16 v[106:107], v206 offset:0x1800
	ds_read_b64_tr_b16 v[108:109], v206 offset:0x2000
	ds_read_b64_tr_b16 v[110:111], v206 offset:0x2800
	ds_read_b64_tr_b16 v[220:221], v206 offset:0x3000
	ds_read_b64_tr_b16 v[222:223], v206 offset:0x3800
	s_waitcnt lgkmcnt(0)
	s_nop 0
	v_mfma_f32_32x32x16_bf16 v[0:15], v[64:67], v[100:103], v[0:15]
	ds_read_b64_tr_b16 v[100:101], v206 offset:0x200
	ds_read_b64_tr_b16 v[102:103], v206 offset:0xa00
	v_mfma_f32_32x32x16_bf16 v[0:15], v[68:71], v[104:107], v[0:15]
	ds_read_b64_tr_b16 v[104:105], v206 offset:0x1200
	ds_read_b64_tr_b16 v[106:107], v206 offset:0x1a00
	v_mfma_f32_32x32x16_bf16 v[0:15], v[72:75], v[108:111], v[0:15]
	ds_read_b64_tr_b16 v[108:109], v206 offset:0x2200
	ds_read_b64_tr_b16 v[110:111], v206 offset:0x2a00
	v_mfma_f32_32x32x16_bf16 v[0:15], v[76:79], v[220:223], v[0:15]
	ds_read_b64_tr_b16 v[220:221], v206 offset:0x3200
	ds_read_b64_tr_b16 v[222:223], v206 offset:0x3a00
	s_waitcnt lgkmcnt(0)
; #define NOP_() do { } while (0)
; __device__ __forceinline__ void partialSM(f32x16& p0, f32x16& p1, float& m_reg, float& mn, float& alpha) {
;     ...
;   for (int r = 0; r < 16; ++r) p0[r] = p0[r] - mn; for (int r = 0; r < 16; ++r) p1[r] = p1[r] - mn;
;   for (int r = 0; r < 16; ++r) p0[r] = __builtin_amdgcn_exp2f(p0[r]);
; }
; __device__ __forceinline__ void partialSM_fixed(f32x16& p0) {
;   for (int r = 0; r < 16; ++r) p0[r] = __builtin_amdgcn_exp2f(p0[r]);
; }
; __device__ __forceinline__ void finishSM(f32x16& p0, f32x16& p1, float alpha, float& l_reg, bf16x8& pa0, bf16x8& pa1, bf16x8& pa2, bf16x8& pa3) {
;   for (int r = 0; r < 16; ++r) p1[r] = __builtin_amdgcn_exp2f(p1[r]);
;   float ps = 0; for (int r = 0; r < 16; ++r) ps += p0[r]; for (int r = 0; r < 16; ++r) ps += p1[r];
;   { auto rr = __builtin_amdgcn_permlane32_swap(__float_as_uint(ps), __float_as_uint(ps), false, false);
;     ps = __uint_as_float(rr[0]) + __uint_as_float(rr[1]); }
;   l_reg = l_reg * alpha + ps;
;     ...
;   PK4(p0, 0, pa0); PK4(p0, 8, pa1); PK4(p1, 0, pa2); PK4(p1, 8, pa3);
;     ...
; }
; template <bool PARTIAL, bool FIXED> ...
;     ...
;   HALF_A(2, 1, do { if (mask_last) { asm volatile("; masked tail tile" ::: "memory"); const float NEG = -INFINITY; \
;       _Pragma("unroll") for (int r = 8; r < 16; ++r) pA0[r] = NEG; _Pragma("unroll") for (int r = 0; r < 16; ++r) pA1[r] = NEG; } } while (0), NOP_(), NOP_());
	v_mfma_f32_32x32x16_bf16 v[16:31], v[64:67], v[100:103], v[16:31]
	ds_read_b64_tr_b16 v[100:101], v206 offset:0x400
	ds_read_b64_tr_b16 v[102:103], v206 offset:0xc00
	v_mfma_f32_32x32x16_bf16 v[16:31], v[68:71], v[104:107], v[16:31]
	ds_read_b64_tr_b16 v[104:105], v206 offset:0x1400
	ds_read_b64_tr_b16 v[106:107], v206 offset:0x1c00
	v_mfma_f32_32x32x16_bf16 v[16:31], v[72:75], v[108:111], v[16:31]
	ds_read_b64_tr_b16 v[108:109], v206 offset:0x2400
	ds_read_b64_tr_b16 v[110:111], v206 offset:0x2c00
	v_mfma_f32_32x32x16_bf16 v[16:31], v[76:79], v[220:223], v[16:31]
	ds_read_b64_tr_b16 v[220:221], v206 offset:0x3400
	ds_read_b64_tr_b16 v[222:223], v206 offset:0x3c00
	s_waitcnt lgkmcnt(0)
	v_mfma_f32_32x32x16_bf16 v[32:47], v[64:67], v[100:103], v[32:47]
	ds_read_b64_tr_b16 v[100:101], v206 offset:0x600
	ds_read_b64_tr_b16 v[102:103], v206 offset:0xe00
	v_mfma_f32_32x32x16_bf16 v[32:47], v[68:71], v[104:107], v[32:47]
	ds_read_b64_tr_b16 v[104:105], v206 offset:0x1600
	ds_read_b64_tr_b16 v[106:107], v206 offset:0x1e00
	v_mfma_f32_32x32x16_bf16 v[32:47], v[72:75], v[108:111], v[32:47]
	ds_read_b64_tr_b16 v[108:109], v206 offset:0x2600
	ds_read_b64_tr_b16 v[110:111], v206 offset:0x2e00
	v_mfma_f32_32x32x16_bf16 v[32:47], v[76:79], v[220:223], v[32:47]
	ds_read_b64_tr_b16 v[220:221], v206 offset:0x3600
	ds_read_b64_tr_b16 v[222:223], v206 offset:0x3e00
	s_waitcnt lgkmcnt(0)
	v_mfma_f32_32x32x16_bf16 v[48:63], v[64:67], v[100:103], v[48:63]
	s_waitcnt vmcnt(5)
	ds_write_b128 v211, v[146:149] offset:32768
	s_waitcnt vmcnt(3)
	ds_write_b128 v212, v[150:153] offset:32768
	ds_write_b128 v213, v[154:157] offset:32768
	s_waitcnt vmcnt(2)
	ds_write_b128 v214, v[158:161] offset:32768
	s_waitcnt lgkmcnt(0)
	s_barrier
	v_mfma_f32_32x32x16_bf16 v[48:63], v[68:71], v[104:107], v[48:63]
	v_mfma_f32_32x32x16_bf16 v[48:63], v[72:75], v[108:111], v[48:63]
	v_mfma_f32_32x32x16_bf16 v[48:63], v[76:79], v[220:223], v[48:63]
	ds_read_b128 v[64:67], v207 offset:32768
	ds_read_b128 v[100:103], v208 offset:32768
	s_add_i32 s2, 0, 0x18000
	s_waitcnt lgkmcnt(1)
	v_mfma_f32_32x32x16_bf16 v[64:79], v[64:67], v[142:145], 0
	s_waitcnt lgkmcnt(0)
	v_mfma_f32_32x32x16_bf16 v[64:79], v[100:103], v[138:141], v[64:79]
	ds_read_b128 v[100:103], v209 offset:32768
	s_waitcnt lgkmcnt(0)
	v_mfma_f32_32x32x16_bf16 v[64:79], v[100:103], v[112:115], v[64:79]
	ds_read_b128 v[100:103], v210 offset:32768
	s_waitcnt lgkmcnt(0)
	v_mfma_f32_32x32x16_bf16 v[64:79], v[100:103], v[116:119], v[64:79]
	ds_read_b128 v[100:103], v190 offset:32768
	s_waitcnt lgkmcnt(0)
	v_mfma_f32_32x32x16_bf16 v[64:79], v[100:103], v[120:123], v[64:79]
	ds_read_b128 v[100:103], v191 offset:32768
	s_waitcnt lgkmcnt(0)
	v_mfma_f32_32x32x16_bf16 v[64:79], v[100:103], v[124:127], v[64:79]
	ds_read_b128 v[100:103], v192 offset:32768
	s_waitcnt lgkmcnt(0)
	v_mfma_f32_32x32x16_bf16 v[64:79], v[100:103], v[130:133], v[64:79]
	ds_read_b128 v[100:103], v193 offset:32768
	s_waitcnt lgkmcnt(0)
	v_and_b32_e32 v190, 63, v195
	v_lshlrev_b32_e32 v191, 4, v195
	v_and_b32_e32 v192, 31, v195
	v_bfe_u32 v193, v195, 5, 1
	v_mfma_f32_32x32x16_bf16 v[64:79], v[100:103], v[134:137], v[64:79]
	v_mfma_f32_32x32x16_bf16 v[96:111], v[96:99], v[142:145], 0
	s_nop 10
	v_exp_f32_e32 v72, v80
	v_exp_f32_e32 v80, v81
	v_exp_f32_e32 v73, v82
	v_exp_f32_e32 v81, v83
	v_exp_f32_e32 v74, v84
	v_add_f32_e32 v84, 0, v72
	v_exp_f32_e32 v82, v85
	v_mfma_f32_32x32x16_bf16 v[96:111], v[170:173], v[138:141], v[96:111]
	v_add_f32_e32 v84, v80, v84
	v_exp_f32_e32 v75, v86
	v_add_f32_e32 v84, v73, v84
	v_exp_f32_e32 v83, v87
	v_add_f32_e32 v84, v81, v84
	v_exp_f32_e32 v76, v88
	v_add_f32_e32 v84, v74, v84
	v_mfma_f32_32x32x16_bf16 v[96:111], v[162:165], v[112:115], v[96:111]
	v_exp_f32_e32 v85, v89
	v_add_f32_e32 v84, v82, v84
	v_exp_f32_e32 v77, v90
	v_add_f32_e32 v84, v75, v84
	v_exp_f32_e32 v87, v91
	v_add_f32_e32 v84, v83, v84
	v_exp_f32_e32 v78, v92
	v_mfma_f32_32x32x16_bf16 v[96:111], v[166:169], v[116:119], v[96:111]
	v_add_f32_e32 v84, v76, v84
	v_exp_f32_e32 v89, v93
	v_add_f32_e32 v84, v85, v84
	v_exp_f32_e32 v79, v94
	v_add_f32_e32 v84, v77, v84
	v_exp_f32_e32 v90, v95
	v_add_f32_e32 v84, v87, v84
	v_mfma_f32_32x32x16_bf16 v[96:111], v[174:177], v[120:123], v[96:111]
	v_add_f32_e32 v84, v78, v84
	v_add_f32_e32 v84, v89, v84
	v_add_f32_e32 v84, v79, v84
	v_add_f32_e32 v84, v90, v84
	v_lshl_add_u32 v88, v247, 2, s2
	v_cvt_pk_bf16_f32 v72, v72, v80
	v_cvt_pk_bf16_f32 v73, v73, v81
	v_mfma_f32_32x32x16_bf16 v[96:111], v[178:181], v[124:127], v[96:111]
	v_cvt_pk_bf16_f32 v74, v74, v82
	v_cvt_pk_bf16_f32 v75, v75, v83
	v_cvt_pk_bf16_f32 v76, v76, v85
	v_cvt_pk_bf16_f32 v77, v77, v87
	v_cvt_pk_bf16_f32 v78, v78, v89
	v_cvt_pk_bf16_f32 v79, v79, v90
	s_nop 0
	v_permlane32_swap_b32_e32 v72, v74
	v_mfma_f32_32x32x16_bf16 v[96:111], v[182:185], v[130:133], v[96:111]
	v_permlane32_swap_b32_e32 v73, v75
	v_permlane32_swap_b32_e32 v76, v78
	v_permlane32_swap_b32_e32 v77, v79
	v_mfma_f32_32x32x16_bf16 v[96:111], v[186:189], v[134:137], v[96:111]
	s_nop 11
	v_exp_f32_e32 v91, v96
	v_exp_f32_e32 v92, v97
	v_exp_f32_e32 v93, v98
	v_exp_f32_e32 v94, v99
	v_exp_f32_e32 v95, v100
	v_add_f32_e32 v84, v84, v91
	v_exp_f32_e32 v96, v101
	v_add_f32_e32 v84, v92, v84
	v_exp_f32_e32 v97, v102
	v_add_f32_e32 v84, v93, v84
	v_exp_f32_e32 v98, v103
	v_add_f32_e32 v84, v94, v84
	v_exp_f32_e32 v99, v104
	v_add_f32_e32 v84, v95, v84
	v_exp_f32_e32 v100, v105
	v_add_f32_e32 v84, v96, v84
	v_exp_f32_e32 v101, v106
	v_add_f32_e32 v84, v97, v84
	v_exp_f32_e32 v102, v107
	v_add_f32_e32 v84, v98, v84
	v_exp_f32_e32 v103, v108
	v_add_f32_e32 v84, v99, v84
	v_exp_f32_e32 v104, v109
	v_add_f32_e32 v84, v100, v84
	v_exp_f32_e32 v105, v110
	v_add_f32_e32 v84, v101, v84
	v_exp_f32_e32 v106, v111
	v_add_f32_e32 v84, v102, v84
	v_add_f32_e32 v84, v103, v84
	v_add_f32_e32 v84, v104, v84
	v_add_f32_e32 v84, v105, v84
	v_add_f32_e32 v84, v106, v84
	v_mov_b32_e32 v86, v84
	s_nop 1
	v_permlane32_swap_b32_e32 v84, v86
	v_cvt_pk_bf16_f32 v80, v91, v92
	v_cvt_pk_bf16_f32 v81, v93, v94
	v_cvt_pk_bf16_f32 v82, v95, v96
	v_cvt_pk_bf16_f32 v83, v97, v98
	v_cvt_pk_bf16_f32 v90, v99, v100
	v_cvt_pk_bf16_f32 v91, v101, v102
	v_cvt_pk_bf16_f32 v92, v103, v104
	v_cvt_pk_bf16_f32 v93, v105, v106
	s_nop 0
	v_permlane32_swap_b32_e32 v80, v82
	v_permlane32_swap_b32_e32 v81, v83
	v_permlane32_swap_b32_e32 v90, v92
	v_permlane32_swap_b32_e32 v91, v93
	ds_read_b64_tr_b16 v[94:95], v206 offset:0x4000
	ds_read_b64_tr_b16 v[96:97], v206 offset:0x4800
	ds_read_b64_tr_b16 v[98:99], v206 offset:0x5000
	ds_read_b64_tr_b16 v[100:101], v206 offset:0x5800
	ds_read_b64_tr_b16 v[102:103], v206 offset:0x6000
	ds_read_b64_tr_b16 v[104:105], v206 offset:0x6800
	ds_read_b64_tr_b16 v[106:107], v206 offset:0x7000
	ds_read_b64_tr_b16 v[108:109], v206 offset:0x7800
	s_waitcnt lgkmcnt(0)
; #define SBAR() __builtin_amdgcn_sched_barrier(0)
; __device__ __forceinline__ int crow(int r, int hi) { return (r & 3) + 8 * (r >> 2) + 4 * hi; }
; #define NOP_() do { } while (0)
; template <bool PARTIAL, bool FIXED> ...
;     ...
;   HALF_A(2, 1, do { if (mask_last) { asm volatile("; masked tail tile" ::: "memory"); const float NEG = -INFINITY; \
;       _Pragma("unroll") for (int r = 8; r < 16; ++r) pA0[r] = NEG; _Pragma("unroll") for (int r = 0; r < 16; ++r) pA1[r] = NEG; } } while (0), NOP_(), NOP_());
;     ...
;   SBAR(); finishSM(pA0, pA1, alA, l_reg, pa0, pa1, pa2, pa3); SBAR();
;   pv_i<2 * 16384>(o, vbi, pa0, pa1, pa2, pa3);
;     ...
;   if (PARTIAL) {
;     if (wid < 2) { float* po = PO + (wid * QBLK) * 128;
; #pragma unroll
;       for (int r = 0; r < 16; ++r) { const int orow = crow(r, hi);
; #pragma unroll
;         for (int d0 = 0; d0 < 4; ++d0) po[orow * 128 + d0 * 32 + r32] = o[d0][r]; }
;       if (hi == 0) { PO[8192 + (wid * QBLK + r32) * 2] = m_reg; PO[8192 + (wid * QBLK + r32) * 2 + 1] = l_reg; } }
;     __syncthreads();
;     return;
;   }
;   if (hi == 0) li_l[r32] = l_reg; asm volatile("s_waitcnt lgkmcnt(0)" ::: "memory");
	s_nop 0
	v_mfma_f32_32x32x16_bf16 v[0:15], v[72:75], v[94:97], v[0:15]
	ds_read_b64_tr_b16 v[94:95], v206 offset:0x4200
	ds_read_b64_tr_b16 v[96:97], v206 offset:0x4a00
	v_mfma_f32_32x32x16_bf16 v[0:15], v[76:79], v[98:101], v[0:15]
	ds_read_b64_tr_b16 v[98:99], v206 offset:0x5200
	ds_read_b64_tr_b16 v[100:101], v206 offset:0x5a00
	v_mfma_f32_32x32x16_bf16 v[0:15], v[80:83], v[102:105], v[0:15]
	ds_read_b64_tr_b16 v[102:103], v206 offset:0x6200
	ds_read_b64_tr_b16 v[104:105], v206 offset:0x6a00
	v_mfma_f32_32x32x16_bf16 v[0:15], v[90:93], v[106:109], v[0:15]
	ds_read_b64_tr_b16 v[106:107], v206 offset:0x7200
	ds_read_b64_tr_b16 v[108:109], v206 offset:0x7a00
	s_waitcnt lgkmcnt(0)
	v_mfma_f32_32x32x16_bf16 v[16:31], v[72:75], v[94:97], v[16:31]
	ds_read_b64_tr_b16 v[94:95], v206 offset:0x4400
	ds_read_b64_tr_b16 v[96:97], v206 offset:0x4c00
	v_mfma_f32_32x32x16_bf16 v[16:31], v[76:79], v[98:101], v[16:31]
	ds_read_b64_tr_b16 v[98:99], v206 offset:0x5400
	ds_read_b64_tr_b16 v[100:101], v206 offset:0x5c00
	v_mfma_f32_32x32x16_bf16 v[16:31], v[80:83], v[102:105], v[16:31]
	ds_read_b64_tr_b16 v[102:103], v206 offset:0x6400
	ds_read_b64_tr_b16 v[104:105], v206 offset:0x6c00
	v_mfma_f32_32x32x16_bf16 v[16:31], v[90:93], v[106:109], v[16:31]
	ds_read_b64_tr_b16 v[106:107], v206 offset:0x7400
	ds_read_b64_tr_b16 v[108:109], v206 offset:0x7c00
	s_waitcnt lgkmcnt(0)
	v_mfma_f32_32x32x16_bf16 v[32:47], v[72:75], v[94:97], v[32:47]
	ds_read_b64_tr_b16 v[94:95], v206 offset:0x4600
	ds_read_b64_tr_b16 v[96:97], v206 offset:0x4e00
	v_mfma_f32_32x32x16_bf16 v[32:47], v[76:79], v[98:101], v[32:47]
	ds_read_b64_tr_b16 v[98:99], v206 offset:0x5600
	ds_read_b64_tr_b16 v[100:101], v206 offset:0x5e00
	v_mfma_f32_32x32x16_bf16 v[32:47], v[80:83], v[102:105], v[32:47]
	ds_read_b64_tr_b16 v[102:103], v206 offset:0x6600
	ds_read_b64_tr_b16 v[104:105], v206 offset:0x6e00
	v_mfma_f32_32x32x16_bf16 v[32:47], v[90:93], v[106:109], v[32:47]
	ds_read_b64_tr_b16 v[106:107], v206 offset:0x7600
	ds_read_b64_tr_b16 v[108:109], v206 offset:0x7e00
	s_waitcnt lgkmcnt(0)
	v_mfma_f32_32x32x16_bf16 v[48:63], v[72:75], v[94:97], v[48:63]
	v_exp_f32_e32 v64, v64
	v_exp_f32_e32 v65, v65
	v_exp_f32_e32 v66, v66
	v_exp_f32_e32 v67, v67
	v_exp_f32_e32 v68, v68
	v_exp_f32_e32 v69, v69
	v_exp_f32_e32 v70, v70
	v_mfma_f32_32x32x16_bf16 v[48:63], v[76:79], v[98:101], v[48:63]
	v_exp_f32_e32 v71, v71
	v_mfma_f32_32x32x16_bf16 v[48:63], v[80:83], v[102:105], v[48:63]
	v_mfma_f32_32x32x16_bf16 v[48:63], v[90:93], v[106:109], v[48:63]
	v_add_f32_e32 v72, 0, v64
	v_add_f32_e32 v72, v65, v72
	v_add_f32_e32 v72, v66, v72
	v_add_f32_e32 v72, v67, v72
	v_add_f32_e32 v72, v68, v72
	v_add_f32_e32 v72, v69, v72
	v_add_f32_e32 v72, v70, v72
	v_add_f32_e32 v72, v71, v72
	v_add_f32_e32 v85, 0, v72
	v_mov_b32_e32 v87, v85
	s_nop 1
	v_permlane32_swap_b32_e32 v85, v87
	v_cvt_pk_bf16_f32 v64, v64, v65
	v_cvt_pk_bf16_f32 v65, v66, v67
	v_cvt_pk_bf16_f32 v66, v68, v69
	v_cvt_pk_bf16_f32 v67, v70, v71
	v_cvt_pk_bf16_f32 v68, v129, v129
	v_cvt_pk_bf16_f32 v69, v129, v129
	v_cvt_pk_bf16_f32 v70, v129, v129
	v_cvt_pk_bf16_f32 v71, v129, v129
	v_cvt_pk_bf16_f32 v72, v129, v129
	v_cvt_pk_bf16_f32 v73, v129, v129
	v_cvt_pk_bf16_f32 v74, v129, v129
	v_cvt_pk_bf16_f32 v75, v129, v129
	v_cvt_pk_bf16_f32 v76, v129, v129
	v_cvt_pk_bf16_f32 v77, v129, v129
	v_cvt_pk_bf16_f32 v78, v129, v129
	v_cvt_pk_bf16_f32 v79, v129, v129
	s_nop 0
	v_permlane32_swap_b32_e32 v64, v66
	v_permlane32_swap_b32_e32 v65, v67
	v_permlane32_swap_b32_e32 v68, v70
	v_permlane32_swap_b32_e32 v69, v71
	v_permlane32_swap_b32_e32 v72, v74
	v_permlane32_swap_b32_e32 v73, v75
	v_permlane32_swap_b32_e32 v76, v78
	v_permlane32_swap_b32_e32 v77, v79
	ds_read_b64_tr_b16 v[80:81], v206 offset:0x8000
	ds_read_b64_tr_b16 v[82:83], v206 offset:0x8800
	ds_read_b64_tr_b16 v[90:91], v206 offset:0x9000
	ds_read_b64_tr_b16 v[92:93], v206 offset:0x9800
	ds_read_b64_tr_b16 v[94:95], v206 offset:0xa000
	ds_read_b64_tr_b16 v[96:97], v206 offset:0xa800
	ds_read_b64_tr_b16 v[98:99], v206 offset:0xb000
	ds_read_b64_tr_b16 v[100:101], v206 offset:0xb800
	s_waitcnt lgkmcnt(0)
	s_nop 0
	v_mfma_f32_32x32x16_bf16 v[0:15], v[64:67], v[80:83], v[0:15]
	ds_read_b64_tr_b16 v[80:81], v206 offset:0x8200
	ds_read_b64_tr_b16 v[82:83], v206 offset:0x8a00
	v_mfma_f32_32x32x16_bf16 v[0:15], v[68:71], v[90:93], v[0:15]
	ds_read_b64_tr_b16 v[90:91], v206 offset:0x9200
	ds_read_b64_tr_b16 v[92:93], v206 offset:0x9a00
	v_mfma_f32_32x32x16_bf16 v[0:15], v[72:75], v[94:97], v[0:15]
	ds_read_b64_tr_b16 v[94:95], v206 offset:0xa200
	ds_read_b64_tr_b16 v[96:97], v206 offset:0xaa00
	v_mfma_f32_32x32x16_bf16 v[0:15], v[76:79], v[98:101], v[0:15]
	ds_read_b64_tr_b16 v[98:99], v206 offset:0xb200
	ds_read_b64_tr_b16 v[100:101], v206 offset:0xba00
	s_waitcnt lgkmcnt(0)
	v_mfma_f32_32x32x16_bf16 v[16:31], v[64:67], v[80:83], v[16:31]
	ds_read_b64_tr_b16 v[80:81], v206 offset:0x8400
	ds_read_b64_tr_b16 v[82:83], v206 offset:0x8c00
	v_mfma_f32_32x32x16_bf16 v[16:31], v[68:71], v[90:93], v[16:31]
	ds_read_b64_tr_b16 v[90:91], v206 offset:0x9400
	ds_read_b64_tr_b16 v[92:93], v206 offset:0x9c00
	v_mfma_f32_32x32x16_bf16 v[16:31], v[72:75], v[94:97], v[16:31]
	ds_read_b64_tr_b16 v[94:95], v206 offset:0xa400
	ds_read_b64_tr_b16 v[96:97], v206 offset:0xac00
	v_mfma_f32_32x32x16_bf16 v[16:31], v[76:79], v[98:101], v[16:31]
	ds_read_b64_tr_b16 v[98:99], v206 offset:0xb400
	ds_read_b64_tr_b16 v[100:101], v206 offset:0xbc00
	s_waitcnt lgkmcnt(0)
	v_mfma_f32_32x32x16_bf16 v[32:47], v[64:67], v[80:83], v[32:47]
	ds_read_b64_tr_b16 v[80:81], v206 offset:0x8600
	ds_read_b64_tr_b16 v[82:83], v206 offset:0x8e00
	v_mfma_f32_32x32x16_bf16 v[32:47], v[68:71], v[90:93], v[32:47]
	ds_read_b64_tr_b16 v[90:91], v206 offset:0x9600
	ds_read_b64_tr_b16 v[92:93], v206 offset:0x9e00
	v_mfma_f32_32x32x16_bf16 v[32:47], v[72:75], v[94:97], v[32:47]
	ds_read_b64_tr_b16 v[94:95], v206 offset:0xa600
	ds_read_b64_tr_b16 v[96:97], v206 offset:0xae00
	v_mfma_f32_32x32x16_bf16 v[32:47], v[76:79], v[98:101], v[32:47]
	ds_read_b64_tr_b16 v[98:99], v206 offset:0xb600
	ds_read_b64_tr_b16 v[100:101], v206 offset:0xbe00
	s_waitcnt lgkmcnt(0)
	v_mfma_f32_32x32x16_bf16 v[48:63], v[64:67], v[80:83], v[48:63]
	v_cmp_gt_u32_e32 vcc, 32, v190
	v_mfma_f32_32x32x16_bf16 v[48:63], v[68:71], v[90:93], v[48:63]
	v_mfma_f32_32x32x16_bf16 v[48:63], v[72:75], v[94:97], v[48:63]
	v_mfma_f32_32x32x16_bf16 v[48:63], v[76:79], v[98:101], v[48:63]
	s_and_saveexec_b64 s[28:29], vcc
	s_cbranch_execz .LBB0_309
	v_add_f32_e32 v64, v128, v218
	v_add_f32_e32 v66, v215, v64
	v_pk_add_f32 v[64:65], v[84:85], v[86:87]
	v_lshl_add_u32 v67, v192, 2, v88
	v_add_f32_e32 v64, v66, v64
	v_add_f32_e32 v64, v64, v65
	ds_write_b32 v67, v64
	s_branch .LBB0_309
